# hyena_norm: serialized single loads re-issued 16 at a time behind counted waits; attention bias lookups pipelined 8 deep without exec masking
# speedup vs baseline: 1.0204x; 1.0148x over previous
; __device__ __forceinline__ void attn_phase(const bf16* proj, bf16* mixed, const float* rpb, const float* gain_a, LAS unsigned char* lds, int vb, int nb, int wave, int lane_in) {
;     ...
;         const int qc = 16 * cb + qi, wst = min(max(qc - 8, 0), 48);
;         float mx = -3.0e38f;
; #pragma unroll
;         for (int t = 0; t < 16; ++t) {
;             const int dr = row_start + (t >> 1) - r + 7;
; #pragma unroll
;             for (int e = 0; e < 4; ++e) {
;                 const int kc = blk_start + 16 * (t & 1) + 4 * g + e, dc = min(max(kc - qc + 15, 0), 30);
;                 const bool valid = (kc >= wst) && (kc < wst + 16);
;                 const float v = valid ? sc[t][e] * 0.08838834764831845f + bt[dr * 31 + dc] : -1e30f;
;                 sc[t][e] = v; mx = fmaxf(mx, v);
;             }
;         }
.LBB0_447:
	s_or_b64 exec, exec, vcc
	v_mov_b32_e32 v246, 0xf149f2ca
	v_add_u32_e32 v230, 15, v74
	v_min_u32_e32 v230, 30, v230
	v_lshl_add_u32 v230, v230, 2, v73
	v_add_u32_e32 v231, 15, v75
	v_min_u32_e32 v231, 30, v231
	v_lshl_add_u32 v231, v231, 2, v73
	v_add_u32_e32 v232, 15, v76
	v_min_u32_e32 v232, 30, v232
	v_lshl_add_u32 v232, v232, 2, v73
	v_add_u32_e32 v233, 15, v68
	v_min_u32_e32 v233, 30, v233
	v_lshl_add_u32 v233, v233, 2, v73
	v_add_u32_e32 v234, 15, v69
	v_min_u32_e32 v234, 30, v234
	v_lshl_add_u32 v234, v234, 2, v73
	v_add_u32_e32 v235, 15, v77
	v_min_u32_e32 v235, 30, v235
	v_lshl_add_u32 v235, v235, 2, v73
	v_add_u32_e32 v236, 15, v78
	v_min_u32_e32 v236, 30, v236
	v_lshl_add_u32 v236, v236, 2, v73
	v_add_u32_e32 v237, 15, v79
	v_min_u32_e32 v237, 30, v237
	v_lshl_add_u32 v237, v237, 2, v73
	ds_read_b32 v238, v230 offset:992
	ds_read_b32 v239, v231 offset:992
	ds_read_b32 v240, v232 offset:992
	ds_read_b32 v241, v233 offset:992
	ds_read_b32 v242, v234 offset:992
	ds_read_b32 v243, v235 offset:992
	ds_read_b32 v244, v236 offset:992
	ds_read_b32 v245, v237 offset:992
	s_waitcnt lgkmcnt(7)
	v_fmac_f32_e32 v238, 0x3db504f3, v54
	v_cndmask_b32_e64 v61, v246, v238, s[54:55]
	ds_read_b32 v238, v230 offset:1116
	s_waitcnt lgkmcnt(7)
	v_fmac_f32_e32 v239, 0x3db504f3, v55
	v_cndmask_b32_e64 v60, v246, v239, s[56:57]
	ds_read_b32 v239, v231 offset:1116
	s_waitcnt lgkmcnt(7)
	v_fmac_f32_e32 v240, 0x3db504f3, v56
	v_cndmask_b32_e64 v55, v246, v240, s[58:59]
	ds_read_b32 v240, v232 offset:1116
	s_waitcnt lgkmcnt(7)
	v_fmac_f32_e32 v241, 0x3db504f3, v57
	v_cndmask_b32_e64 v54, v246, v241, s[64:65]
	ds_read_b32 v241, v233 offset:1116
	s_waitcnt lgkmcnt(7)
	v_fmac_f32_e32 v242, 0x3db504f3, v50
	v_cndmask_b32_e64 v57, v246, v242, s[66:67]
	ds_read_b32 v242, v234 offset:1116
	s_waitcnt lgkmcnt(7)
	v_fmac_f32_e32 v243, 0x3db504f3, v51
	v_cndmask_b32_e64 v56, v246, v243, s[68:69]
	ds_read_b32 v243, v235 offset:1116
	s_waitcnt lgkmcnt(7)
	v_fmac_f32_e32 v244, 0x3db504f3, v52
	v_cndmask_b32_e64 v51, v246, v244, s[70:71]
	ds_read_b32 v244, v236 offset:1116
	s_waitcnt lgkmcnt(7)
	v_fmac_f32_e32 v245, 0x3db504f3, v53
	v_cndmask_b32_e64 v50, v246, v245, s[4:5]
	ds_read_b32 v245, v237 offset:1116
	s_waitcnt lgkmcnt(7)
	v_fmac_f32_e32 v238, 0x3db504f3, v46
	v_cndmask_b32_e64 v53, v246, v238, s[54:55]
	ds_read_b32 v238, v230 offset:1240
	s_waitcnt lgkmcnt(7)
	v_fmac_f32_e32 v239, 0x3db504f3, v47
	v_cndmask_b32_e64 v52, v246, v239, s[56:57]
	ds_read_b32 v239, v231 offset:1240
	s_waitcnt lgkmcnt(7)
	v_fmac_f32_e32 v240, 0x3db504f3, v48
	v_cndmask_b32_e64 v47, v246, v240, s[58:59]
	ds_read_b32 v240, v232 offset:1240
	s_waitcnt lgkmcnt(7)
	v_fmac_f32_e32 v241, 0x3db504f3, v49
	v_cndmask_b32_e64 v46, v246, v241, s[64:65]
	ds_read_b32 v241, v233 offset:1240
	s_waitcnt lgkmcnt(7)
	v_fmac_f32_e32 v242, 0x3db504f3, v42
	v_cndmask_b32_e64 v49, v246, v242, s[66:67]
	ds_read_b32 v242, v234 offset:1240
	s_waitcnt lgkmcnt(7)
	v_fmac_f32_e32 v243, 0x3db504f3, v43
	v_cndmask_b32_e64 v48, v246, v243, s[68:69]
	ds_read_b32 v243, v235 offset:1240
	s_waitcnt lgkmcnt(7)
	v_fmac_f32_e32 v244, 0x3db504f3, v44
	v_cndmask_b32_e64 v43, v246, v244, s[70:71]
	ds_read_b32 v244, v236 offset:1240
	s_waitcnt lgkmcnt(7)
	v_fmac_f32_e32 v245, 0x3db504f3, v45
	v_cndmask_b32_e64 v42, v246, v245, s[4:5]
	ds_read_b32 v245, v237 offset:1240
	s_waitcnt lgkmcnt(7)
	v_fmac_f32_e32 v238, 0x3db504f3, v38
	v_cndmask_b32_e64 v45, v246, v238, s[54:55]
	ds_read_b32 v238, v230 offset:1364
	s_waitcnt lgkmcnt(7)
	v_fmac_f32_e32 v239, 0x3db504f3, v39
	v_cndmask_b32_e64 v44, v246, v239, s[56:57]
	ds_read_b32 v239, v231 offset:1364
	s_waitcnt lgkmcnt(7)
	v_fmac_f32_e32 v240, 0x3db504f3, v40
	v_cndmask_b32_e64 v81, v246, v240, s[58:59]
	ds_read_b32 v240, v232 offset:1364
	s_waitcnt lgkmcnt(7)
	v_fmac_f32_e32 v241, 0x3db504f3, v41
	v_cndmask_b32_e64 v80, v246, v241, s[64:65]
	ds_read_b32 v241, v233 offset:1364
	s_waitcnt lgkmcnt(7)
	v_fmac_f32_e32 v242, 0x3db504f3, v34
	v_cndmask_b32_e64 v83, v246, v242, s[66:67]
	ds_read_b32 v242, v234 offset:1364
	s_waitcnt lgkmcnt(7)
	v_fmac_f32_e32 v243, 0x3db504f3, v35
	v_cndmask_b32_e64 v82, v246, v243, s[68:69]
	ds_read_b32 v243, v235 offset:1364
	s_waitcnt lgkmcnt(7)
	v_fmac_f32_e32 v244, 0x3db504f3, v36
	v_cndmask_b32_e64 v85, v246, v244, s[70:71]
	ds_read_b32 v244, v236 offset:1364
	s_waitcnt lgkmcnt(7)
	v_fmac_f32_e32 v245, 0x3db504f3, v37
	v_cndmask_b32_e64 v84, v246, v245, s[4:5]
	ds_read_b32 v245, v237 offset:1364
	s_waitcnt lgkmcnt(7)
	v_fmac_f32_e32 v238, 0x3db504f3, v30
	v_cndmask_b32_e64 v87, v246, v238, s[54:55]
	ds_read_b32 v238, v230 offset:1488
	s_waitcnt lgkmcnt(7)
	v_fmac_f32_e32 v239, 0x3db504f3, v31
	v_cndmask_b32_e64 v86, v246, v239, s[56:57]
	ds_read_b32 v239, v231 offset:1488
	s_waitcnt lgkmcnt(7)
	v_fmac_f32_e32 v240, 0x3db504f3, v32
	v_cndmask_b32_e64 v31, v246, v240, s[58:59]
	ds_read_b32 v240, v232 offset:1488
	s_waitcnt lgkmcnt(7)
	v_fmac_f32_e32 v241, 0x3db504f3, v33
	v_cndmask_b32_e64 v30, v246, v241, s[64:65]
	ds_read_b32 v241, v233 offset:1488
	s_waitcnt lgkmcnt(7)
	v_fmac_f32_e32 v242, 0x3db504f3, v26
	v_cndmask_b32_e64 v33, v246, v242, s[66:67]
	ds_read_b32 v242, v234 offset:1488
	s_waitcnt lgkmcnt(7)
	v_fmac_f32_e32 v243, 0x3db504f3, v27
	v_cndmask_b32_e64 v32, v246, v243, s[68:69]
	ds_read_b32 v243, v235 offset:1488
	s_waitcnt lgkmcnt(7)
	v_fmac_f32_e32 v244, 0x3db504f3, v28
	v_cndmask_b32_e64 v27, v246, v244, s[70:71]
	ds_read_b32 v244, v236 offset:1488
	s_waitcnt lgkmcnt(7)
	v_fmac_f32_e32 v245, 0x3db504f3, v29
	v_cndmask_b32_e64 v26, v246, v245, s[4:5]
	ds_read_b32 v245, v237 offset:1488
	s_waitcnt lgkmcnt(7)
; __device__ __forceinline__ void attn_phase(const bf16* proj, bf16* mixed, const float* rpb, const float* gain_a, LAS unsigned char* lds, int vb, int nb, int wave, int lane_in) {
;     ...
;         const int qc = 16 * cb + qi, wst = min(max(qc - 8, 0), 48);
;         float mx = -3.0e38f;
; #pragma unroll
;         for (int t = 0; t < 16; ++t) {
;             const int dr = row_start + (t >> 1) - r + 7;
; #pragma unroll
;             for (int e = 0; e < 4; ++e) {
;                 const int kc = blk_start + 16 * (t & 1) + 4 * g + e, dc = min(max(kc - qc + 15, 0), 30);
;                 const bool valid = (kc >= wst) && (kc < wst + 16);
;                 const float v = valid ? sc[t][e] * 0.08838834764831845f + bt[dr * 31 + dc] : -1e30f;
;                 sc[t][e] = v; mx = fmaxf(mx, v);
;             }
;         }
;         mx = fmaxf(mx, __shfl_xor(mx, 16)); mx = fmaxf(mx, __shfl_xor(mx, 32));
	v_fmac_f32_e32 v238, 0x3db504f3, v22
	v_cndmask_b32_e64 v29, v246, v238, s[54:55]
	ds_read_b32 v238, v230 offset:1612
	s_waitcnt lgkmcnt(7)
	v_fmac_f32_e32 v239, 0x3db504f3, v23
	v_cndmask_b32_e64 v28, v246, v239, s[56:57]
	ds_read_b32 v239, v231 offset:1612
	s_waitcnt lgkmcnt(7)
	v_fmac_f32_e32 v240, 0x3db504f3, v24
	v_cndmask_b32_e64 v23, v246, v240, s[58:59]
	ds_read_b32 v240, v232 offset:1612
	s_waitcnt lgkmcnt(7)
	v_fmac_f32_e32 v241, 0x3db504f3, v25
	v_cndmask_b32_e64 v22, v246, v241, s[64:65]
	ds_read_b32 v241, v233 offset:1612
	s_waitcnt lgkmcnt(7)
	v_fmac_f32_e32 v242, 0x3db504f3, v18
	v_cndmask_b32_e64 v25, v246, v242, s[66:67]
	ds_read_b32 v242, v234 offset:1612
	s_waitcnt lgkmcnt(7)
	v_fmac_f32_e32 v243, 0x3db504f3, v19
	v_cndmask_b32_e64 v24, v246, v243, s[68:69]
	ds_read_b32 v243, v235 offset:1612
	s_waitcnt lgkmcnt(7)
	v_fmac_f32_e32 v244, 0x3db504f3, v20
	v_cndmask_b32_e64 v19, v246, v244, s[70:71]
	ds_read_b32 v244, v236 offset:1612
	s_waitcnt lgkmcnt(7)
	v_fmac_f32_e32 v245, 0x3db504f3, v21
	v_cndmask_b32_e64 v18, v246, v245, s[4:5]
	ds_read_b32 v245, v237 offset:1612
	s_waitcnt lgkmcnt(7)
	v_fmac_f32_e32 v238, 0x3db504f3, v14
	v_cndmask_b32_e64 v21, v246, v238, s[54:55]
	ds_read_b32 v238, v230 offset:1736
	s_waitcnt lgkmcnt(7)
	v_fmac_f32_e32 v239, 0x3db504f3, v15
	v_cndmask_b32_e64 v20, v246, v239, s[56:57]
	ds_read_b32 v239, v231 offset:1736
	s_waitcnt lgkmcnt(7)
	v_fmac_f32_e32 v240, 0x3db504f3, v16
	v_cndmask_b32_e64 v15, v246, v240, s[58:59]
	ds_read_b32 v240, v232 offset:1736
	s_waitcnt lgkmcnt(7)
	v_fmac_f32_e32 v241, 0x3db504f3, v17
	v_cndmask_b32_e64 v14, v246, v241, s[64:65]
	ds_read_b32 v241, v233 offset:1736
	s_waitcnt lgkmcnt(7)
	v_fmac_f32_e32 v242, 0x3db504f3, v10
	v_cndmask_b32_e64 v17, v246, v242, s[66:67]
	ds_read_b32 v242, v234 offset:1736
	s_waitcnt lgkmcnt(7)
	v_fmac_f32_e32 v243, 0x3db504f3, v11
	v_cndmask_b32_e64 v16, v246, v243, s[68:69]
	ds_read_b32 v243, v235 offset:1736
	s_waitcnt lgkmcnt(7)
	v_fmac_f32_e32 v244, 0x3db504f3, v12
	v_cndmask_b32_e64 v11, v246, v244, s[70:71]
	ds_read_b32 v244, v236 offset:1736
	s_waitcnt lgkmcnt(7)
	v_fmac_f32_e32 v245, 0x3db504f3, v13
	v_cndmask_b32_e64 v10, v246, v245, s[4:5]
	ds_read_b32 v245, v237 offset:1736
	s_waitcnt lgkmcnt(7)
	v_fmac_f32_e32 v238, 0x3db504f3, v6
	v_cndmask_b32_e64 v13, v246, v238, s[54:55]
	s_waitcnt lgkmcnt(6)
	v_fmac_f32_e32 v239, 0x3db504f3, v7
	v_cndmask_b32_e64 v12, v246, v239, s[56:57]
	s_waitcnt lgkmcnt(5)
	v_fmac_f32_e32 v240, 0x3db504f3, v8
	v_cndmask_b32_e64 v7, v246, v240, s[58:59]
	s_waitcnt lgkmcnt(4)
	v_fmac_f32_e32 v241, 0x3db504f3, v9
	v_cndmask_b32_e64 v6, v246, v241, s[64:65]
	s_waitcnt lgkmcnt(3)
	v_fmac_f32_e32 v242, 0x3db504f3, v2
	v_cndmask_b32_e64 v9, v246, v242, s[66:67]
	s_waitcnt lgkmcnt(2)
	v_fmac_f32_e32 v243, 0x3db504f3, v3
	v_cndmask_b32_e64 v8, v246, v243, s[68:69]
	s_waitcnt lgkmcnt(1)
	v_fmac_f32_e32 v244, 0x3db504f3, v4
	v_cndmask_b32_e64 v3, v246, v244, s[70:71]
	s_waitcnt lgkmcnt(0)
	v_fmac_f32_e32 v245, 0x3db504f3, v5
	v_cndmask_b32_e64 v2, v246, v245, s[4:5]
	s_mov_b32 s4, 0xff61b1e6
	v_max3_f32 v4, v63, s4, v62
	v_max3_f32 v4, v4, v65, v64
	v_max3_f32 v4, v4, v67, v66
	v_max3_f32 v4, v4, v59, v58
	v_max3_f32 v4, v4, v61, v60
	v_max3_f32 v4, v4, v55, v54
	v_max3_f32 v4, v4, v57, v56
	v_max3_f32 v4, v4, v51, v50
	v_max3_f32 v4, v4, v53, v52
	v_max3_f32 v4, v4, v47, v46
	v_max3_f32 v4, v4, v49, v48
	v_max3_f32 v4, v4, v43, v42
	v_max3_f32 v4, v4, v45, v44
	v_max3_f32 v4, v4, v81, v80
	v_max3_f32 v4, v4, v83, v82
	v_max3_f32 v4, v4, v85, v84
	v_max3_f32 v4, v4, v87, v86
	v_max3_f32 v4, v4, v31, v30
	v_max3_f32 v4, v4, v33, v32
	v_max3_f32 v4, v4, v27, v26
	v_max3_f32 v4, v4, v29, v28
	v_max3_f32 v4, v4, v23, v22
	v_max3_f32 v4, v4, v25, v24
	v_max3_f32 v4, v4, v19, v18
	v_max3_f32 v4, v4, v21, v20
	v_max3_f32 v4, v4, v15, v14
	v_max3_f32 v4, v4, v17, v16
	v_max3_f32 v4, v4, v11, v10
	v_and_b32_e32 v34, 64, v223
	v_max3_f32 v4, v4, v13, v12
	v_xor_b32_e32 v5, 16, v223
	v_add_u32_e32 v34, 64, v34
	v_max3_f32 v4, v4, v7, v6
	v_cmp_lt_i32_e32 vcc, v5, v34
	v_max3_f32 v4, v4, v9, v8
	v_max3_f32 v4, v4, v3, v2
	v_cndmask_b32_e32 v5, v223, v5, vcc
	v_lshlrev_b32_e32 v95, 2, v5
	ds_bpermute_b32 v5, v95, v4
	v_mov_b64_e32 v[88:89], s[6:7]
	s_waitcnt lgkmcnt(0)
	v_max_f32_e32 v5, v5, v5
	v_max_f32_e32 v4, v4, v5
	v_xor_b32_e32 v5, 32, v223
	v_cmp_lt_i32_e32 vcc, v5, v34
	s_nop 1
	v_cndmask_b32_e32 v5, v223, v5, vcc
	v_lshlrev_b32_e32 v96, 2, v5
	ds_bpermute_b32 v5, v96, v4
	s_waitcnt lgkmcnt(0)
; __device__ __forceinline__ void attn_phase(const bf16* proj, bf16* mixed, const float* rpb, const float* gain_a, LAS unsigned char* lds, int vb, int nb, int wave, int lane_in) {
;     ...
;         float sum = 0.f;
; #pragma unroll
;         for (int t = 0; t < 16; ++t)
; #pragma unroll
;             for (int e = 0; e < 4; ++e) { const float p = __expf(sc[t][e] - mx); sc[t][e] = p; sum += p; }
	v_max_f32_e32 v5, v5, v5
	v_max_f32_e32 v4, v4, v5
	v_sub_f32_e32 v5, v63, v4
	v_mul_f32_e32 v5, 0x3fb8aa3b, v5
	v_sub_f32_e32 v35, v62, v4
	v_exp_f32_e32 v34, v5
	v_mul_f32_e32 v35, 0x3fb8aa3b, v35
	v_sub_f32_e32 v36, v65, v4
	v_exp_f32_e32 v35, v35
	v_mul_f32_e32 v36, 0x3fb8aa3b, v36
	v_sub_f32_e32 v37, v64, v4
	v_exp_f32_e32 v36, v36
	v_mul_f32_e32 v37, 0x3fb8aa3b, v37
	v_sub_f32_e32 v38, v67, v4
	v_exp_f32_e32 v37, v37
	v_mul_f32_e32 v38, 0x3fb8aa3b, v38
	v_sub_f32_e32 v39, v66, v4
	v_add_f32_e32 v5, 0, v34
	v_exp_f32_e32 v38, v38
	v_mul_f32_e32 v39, 0x3fb8aa3b, v39
	v_sub_f32_e32 v40, v59, v4
	v_add_f32_e32 v5, v35, v5
	v_exp_f32_e32 v39, v39
	v_mul_f32_e32 v40, 0x3fb8aa3b, v40
	v_sub_f32_e32 v41, v58, v4
	v_sub_f32_e32 v58, v61, v4
	v_add_f32_e32 v5, v36, v5
	v_exp_f32_e32 v40, v40
	v_mul_f32_e32 v41, 0x3fb8aa3b, v41
	v_mul_f32_e32 v58, 0x3fb8aa3b, v58
	v_add_f32_e32 v5, v37, v5
	v_exp_f32_e32 v41, v41
	v_exp_f32_e32 v162, v58
	v_sub_f32_e32 v58, v60, v4
	v_sub_f32_e32 v54, v54, v4
	v_add_f32_e32 v5, v38, v5
	v_mul_f32_e32 v58, 0x3fb8aa3b, v58
	v_sub_f32_e32 v55, v55, v4
	v_mul_f32_e32 v54, 0x3fb8aa3b, v54
	v_add_f32_e32 v5, v39, v5
	v_exp_f32_e32 v163, v58
	v_mul_f32_e32 v55, 0x3fb8aa3b, v55
	v_exp_f32_e32 v165, v54
	v_sub_f32_e32 v54, v57, v4
	v_add_f32_e32 v5, v40, v5
	v_exp_f32_e32 v164, v55
	v_mul_f32_e32 v54, 0x3fb8aa3b, v54
	v_add_f32_e32 v5, v41, v5
	v_exp_f32_e32 v166, v54
	v_sub_f32_e32 v54, v56, v4
	v_sub_f32_e32 v50, v50, v4
	v_sub_f32_e32 v42, v42, v4
	v_add_f32_e32 v5, v162, v5
	v_mul_f32_e32 v54, 0x3fb8aa3b, v54
	v_sub_f32_e32 v51, v51, v4
	v_mul_f32_e32 v50, 0x3fb8aa3b, v50
	v_mul_f32_e32 v42, 0x3fb8aa3b, v42
	v_add_f32_e32 v5, v163, v5
	v_exp_f32_e32 v167, v54
	v_mul_f32_e32 v51, 0x3fb8aa3b, v51
	v_exp_f32_e32 v169, v50
	v_sub_f32_e32 v50, v53, v4
	v_exp_f32_e32 v161, v42
	v_sub_f32_e32 v42, v45, v4
	v_add_f32_e32 v5, v164, v5
	v_exp_f32_e32 v168, v51
	v_mul_f32_e32 v50, 0x3fb8aa3b, v50
	v_mul_f32_e32 v42, 0x3fb8aa3b, v42
	v_add_f32_e32 v5, v165, v5
	v_exp_f32_e32 v154, v50
	v_sub_f32_e32 v50, v52, v4
	v_sub_f32_e32 v46, v46, v4
	v_exp_f32_e32 v145, v42
	v_sub_f32_e32 v42, v44, v4
	v_add_f32_e32 v5, v166, v5
	v_mul_f32_e32 v50, 0x3fb8aa3b, v50
	v_sub_f32_e32 v47, v47, v4
	v_mul_f32_e32 v46, 0x3fb8aa3b, v46
	v_mul_f32_e32 v42, 0x3fb8aa3b, v42
	v_add_f32_e32 v5, v167, v5
	v_exp_f32_e32 v155, v50
	v_mul_f32_e32 v47, 0x3fb8aa3b, v47
	v_exp_f32_e32 v157, v46
	v_sub_f32_e32 v46, v49, v4
	v_exp_f32_e32 v147, v42
	v_sub_f32_e32 v42, v81, v4
	v_add_f32_e32 v5, v168, v5
	v_exp_f32_e32 v156, v47
	v_mul_f32_e32 v46, 0x3fb8aa3b, v46
	v_mul_f32_e32 v42, 0x3fb8aa3b, v42
	v_add_f32_e32 v5, v169, v5
	v_exp_f32_e32 v158, v46
	v_sub_f32_e32 v46, v48, v4
	v_exp_f32_e32 v148, v42
	v_sub_f32_e32 v42, v80, v4
	v_add_f32_e32 v5, v154, v5
	v_mul_f32_e32 v46, 0x3fb8aa3b, v46
	v_sub_f32_e32 v43, v43, v4
	v_mul_f32_e32 v42, 0x3fb8aa3b, v42
	v_add_f32_e32 v5, v155, v5
	v_exp_f32_e32 v159, v46
	v_mul_f32_e32 v43, 0x3fb8aa3b, v43
	v_exp_f32_e32 v149, v42
	v_sub_f32_e32 v42, v83, v4
	v_add_f32_e32 v5, v156, v5
	v_exp_f32_e32 v160, v43
	v_mul_f32_e32 v42, 0x3fb8aa3b, v42
	v_add_f32_e32 v5, v157, v5
	v_exp_f32_e32 v150, v42
	v_sub_f32_e32 v42, v82, v4
	v_add_f32_e32 v5, v158, v5
	v_mul_f32_e32 v42, 0x3fb8aa3b, v42
	v_add_f32_e32 v5, v159, v5
	v_exp_f32_e32 v151, v42
	v_sub_f32_e32 v42, v85, v4
	v_add_f32_e32 v5, v160, v5
	v_mul_f32_e32 v42, 0x3fb8aa3b, v42
	v_add_f32_e32 v5, v161, v5
	v_exp_f32_e32 v152, v42
	v_sub_f32_e32 v42, v84, v4
	v_add_f32_e32 v5, v145, v5
	v_mul_f32_e32 v42, 0x3fb8aa3b, v42
	v_add_f32_e32 v5, v147, v5
	v_exp_f32_e32 v153, v42
	v_sub_f32_e32 v42, v87, v4
	v_add_f32_e32 v5, v148, v5
	v_mul_f32_e32 v42, 0x3fb8aa3b, v42
	v_add_f32_e32 v5, v149, v5
	v_exp_f32_e32 v129, v42
	v_sub_f32_e32 v42, v86, v4
	v_sub_f32_e32 v30, v30, v4
	v_add_f32_e32 v5, v150, v5
	v_mul_f32_e32 v42, 0x3fb8aa3b, v42
	v_sub_f32_e32 v31, v31, v4
	v_mul_f32_e32 v30, 0x3fb8aa3b, v30
	v_add_f32_e32 v5, v151, v5
	v_exp_f32_e32 v130, v42
	v_mul_f32_e32 v31, 0x3fb8aa3b, v31
	v_exp_f32_e32 v132, v30
	v_sub_f32_e32 v30, v33, v4
	v_add_f32_e32 v5, v152, v5
	v_exp_f32_e32 v131, v31
	v_mul_f32_e32 v30, 0x3fb8aa3b, v30
	v_add_f32_e32 v5, v153, v5
	v_exp_f32_e32 v133, v30
	v_sub_f32_e32 v30, v32, v4
	v_sub_f32_e32 v26, v26, v4
	v_add_f32_e32 v5, v129, v5
	v_mul_f32_e32 v30, 0x3fb8aa3b, v30
	v_sub_f32_e32 v27, v27, v4
	v_mul_f32_e32 v26, 0x3fb8aa3b, v26
	v_add_f32_e32 v5, v130, v5
	v_exp_f32_e32 v134, v30
	v_mul_f32_e32 v27, 0x3fb8aa3b, v27
	v_exp_f32_e32 v136, v26
	v_sub_f32_e32 v26, v29, v4
	v_add_f32_e32 v5, v131, v5
	v_exp_f32_e32 v135, v27
	v_mul_f32_e32 v26, 0x3fb8aa3b, v26
	v_add_f32_e32 v5, v132, v5
	v_exp_f32_e32 v120, v26
	v_sub_f32_e32 v26, v28, v4
	v_sub_f32_e32 v22, v22, v4
	v_add_f32_e32 v5, v133, v5
	v_mul_f32_e32 v26, 0x3fb8aa3b, v26
	v_sub_f32_e32 v23, v23, v4
	v_mul_f32_e32 v22, 0x3fb8aa3b, v22
	v_add_f32_e32 v5, v134, v5
	v_exp_f32_e32 v121, v26
	v_mul_f32_e32 v23, 0x3fb8aa3b, v23
	v_exp_f32_e32 v123, v22
	v_sub_f32_e32 v22, v25, v4
	v_add_f32_e32 v5, v135, v5
	v_exp_f32_e32 v122, v23
	v_mul_f32_e32 v22, 0x3fb8aa3b, v22
	v_add_f32_e32 v5, v136, v5
	v_exp_f32_e32 v124, v22
	v_sub_f32_e32 v22, v24, v4
	v_sub_f32_e32 v18, v18, v4
	v_add_f32_e32 v5, v120, v5
	v_mul_f32_e32 v22, 0x3fb8aa3b, v22
	v_sub_f32_e32 v19, v19, v4
	v_mul_f32_e32 v18, 0x3fb8aa3b, v18
	v_add_f32_e32 v5, v121, v5
	v_exp_f32_e32 v125, v22
	v_mul_f32_e32 v19, 0x3fb8aa3b, v19
	v_exp_f32_e32 v127, v18
	v_sub_f32_e32 v18, v21, v4
	v_add_f32_e32 v5, v122, v5
	v_exp_f32_e32 v126, v19
	v_mul_f32_e32 v18, 0x3fb8aa3b, v18
	v_add_f32_e32 v5, v123, v5
	v_exp_f32_e32 v110, v18
	v_sub_f32_e32 v18, v20, v4
; __device__ __forceinline__ void attn_phase(const bf16* proj, bf16* mixed, const float* rpb, const float* gain_a, LAS unsigned char* lds, int vb, int nb, int wave, int lane_in) {
;     ...
;             for (int e = 0; e < 4; ++e) { const float p = __expf(sc[t][e] - mx); sc[t][e] = p; sum += p; }
;         sum += __shfl_xor(sum, 16); sum += __shfl_xor(sum, 32);
;         f32x4 o[8];
; #pragma unroll
;         for (int v = 0; v < 8; ++v) o[v] = (f32x4){0.f, 0.f, 0.f, 0.f};
;         v4u vr[8];
;         { const int vtok0 = base + 64 * row_start + blk_start;
; #pragma unroll
;           for (int i = 0; i < 8; ++i) { const int id = lane + 64 * i, j = id >> 4, ch = id & 15; vr[i] = *(const v4u*)(proj + (size_t)(vtok0 + j) * NIN + C_AV + h * 128 + ch * 8); } }
	v_sub_f32_e32 v14, v14, v4
	v_add_f32_e32 v5, v124, v5
	v_mul_f32_e32 v18, 0x3fb8aa3b, v18
	v_sub_f32_e32 v15, v15, v4
	v_mul_f32_e32 v14, 0x3fb8aa3b, v14
	v_add_f32_e32 v5, v125, v5
	v_exp_f32_e32 v111, v18
	v_mul_f32_e32 v15, 0x3fb8aa3b, v15
	v_exp_f32_e32 v113, v14
	v_sub_f32_e32 v14, v17, v4
	v_add_f32_e32 v5, v126, v5
	v_exp_f32_e32 v112, v15
	v_mul_f32_e32 v14, 0x3fb8aa3b, v14
	v_add_f32_e32 v5, v127, v5
	v_exp_f32_e32 v114, v14
	v_sub_f32_e32 v14, v16, v4
	v_sub_f32_e32 v10, v10, v4
	v_add_f32_e32 v5, v110, v5
	v_mul_f32_e32 v14, 0x3fb8aa3b, v14
	v_sub_f32_e32 v11, v11, v4
	v_mul_f32_e32 v10, 0x3fb8aa3b, v10
	v_add_f32_e32 v5, v111, v5
	v_exp_f32_e32 v115, v14
	v_mul_f32_e32 v11, 0x3fb8aa3b, v11
	v_exp_f32_e32 v117, v10
	v_sub_f32_e32 v10, v13, v4
	v_add_f32_e32 v5, v112, v5
	v_exp_f32_e32 v116, v11
	v_mul_f32_e32 v10, 0x3fb8aa3b, v10
	v_add_f32_e32 v5, v113, v5
	v_exp_f32_e32 v101, v10
	v_sub_f32_e32 v10, v12, v4
	v_sub_f32_e32 v6, v6, v4
	v_add_f32_e32 v5, v114, v5
	v_mul_f32_e32 v10, 0x3fb8aa3b, v10
	v_sub_f32_e32 v7, v7, v4
	v_mul_f32_e32 v6, 0x3fb8aa3b, v6
	v_add_f32_e32 v5, v115, v5
	v_exp_f32_e32 v102, v10
	v_mul_f32_e32 v7, 0x3fb8aa3b, v7
	v_exp_f32_e32 v104, v6
	v_sub_f32_e32 v6, v9, v4
	v_add_f32_e32 v5, v116, v5
	v_exp_f32_e32 v103, v7
	v_mul_f32_e32 v6, 0x3fb8aa3b, v6
	v_add_f32_e32 v5, v117, v5
	v_exp_f32_e32 v105, v6
	v_sub_f32_e32 v6, v8, v4
	v_add_f32_e32 v5, v101, v5
	v_mul_f32_e32 v6, 0x3fb8aa3b, v6
	v_sub_f32_e32 v3, v3, v4
	v_add_f32_e32 v5, v102, v5
	v_exp_f32_e32 v106, v6
	v_mul_f32_e32 v3, 0x3fb8aa3b, v3
	v_sub_f32_e32 v2, v2, v4
	v_add_f32_e32 v5, v103, v5
	v_exp_f32_e32 v107, v3
	v_mul_f32_e32 v2, 0x3fb8aa3b, v2
	v_add_f32_e32 v5, v104, v5
	v_exp_f32_e32 v108, v2
	v_add_f32_e32 v5, v105, v5
	v_add_f32_e32 v5, v106, v5
	v_add_f32_e32 v3, v107, v5
	v_add_f32_e32 v2, v108, v3
	ds_bpermute_b32 v3, v95, v2
	v_or_b32_e32 v43, s29, v72
	v_add_u32_e32 v30, v128, v43
	v_add_u32_e32 v45, 64, v1
	v_lshlrev_b32_e32 v4, 4, v1
	s_waitcnt lgkmcnt(0)
	v_add_f32_e32 v99, v2, v3
	v_add_u32_e32 v2, v30, v71
	v_mad_i64_i32 v[2:3], s[4:5], v2, s33, v[88:89]
	v_ashrrev_i32_e32 v137, 4, v45
	v_lshl_add_u64 v[2:3], v[2:3], 0, s[42:43]
	v_and_b32_e32 v182, 0xf0, v4
	v_add_u32_e32 v6, v30, v137
	v_add_u32_e32 v46, 0x80, v1
	v_lshl_add_u64 v[2:3], v[2:3], 0, v[182:183]
	v_mad_i64_i32 v[6:7], s[4:5], v6, s33, v[88:89]
	v_ashrrev_i32_e32 v138, 4, v46
	v_add_co_u32_e32 v2, vcc, s25, v2
	v_lshl_add_u64 v[6:7], v[6:7], 0, s[42:43]
	v_add_u32_e32 v10, v30, v138
	v_add_u32_e32 v47, 0xc0, v1
	v_addc_co_u32_e32 v3, vcc, 0, v3, vcc
	v_lshl_add_u64 v[6:7], v[6:7], 0, v[182:183]
	v_mad_i64_i32 v[10:11], s[4:5], v10, s33, v[88:89]
	v_ashrrev_i32_e32 v139, 4, v47
	v_add_co_u32_e32 v6, vcc, s25, v6
	v_lshl_add_u64 v[10:11], v[10:11], 0, s[42:43]
	v_add_u32_e32 v14, v30, v139
	v_add_u32_e32 v48, 0x100, v1
	v_addc_co_u32_e32 v7, vcc, 0, v7, vcc
	v_lshl_add_u64 v[10:11], v[10:11], 0, v[182:183]
	v_mad_i64_i32 v[14:15], s[4:5], v14, s33, v[88:89]
	v_ashrrev_i32_e32 v140, 4, v48
	v_add_co_u32_e32 v10, vcc, s25, v10
	v_lshl_add_u64 v[14:15], v[14:15], 0, s[42:43]
	v_add_u32_e32 v18, v30, v140
	v_add_u32_e32 v49, 0x140, v1
	v_addc_co_u32_e32 v11, vcc, 0, v11, vcc
	v_lshl_add_u64 v[14:15], v[14:15], 0, v[182:183]
	v_mad_i64_i32 v[18:19], s[4:5], v18, s33, v[88:89]
	v_ashrrev_i32_e32 v141, 4, v49
	v_add_co_u32_e32 v14, vcc, s25, v14
	v_lshl_add_u64 v[18:19], v[18:19], 0, s[42:43]
	v_add_u32_e32 v22, v30, v141
	v_add_u32_e32 v50, 0x180, v1
	v_addc_co_u32_e32 v15, vcc, 0, v15, vcc
	v_lshl_add_u64 v[18:19], v[18:19], 0, v[182:183]
	v_mad_i64_i32 v[22:23], s[4:5], v22, s33, v[88:89]
	v_ashrrev_i32_e32 v142, 4, v50
	global_load_dwordx4 v[2:5], v[2:3], off
	v_add_co_u32_e32 v18, vcc, s25, v18
	v_lshl_add_u64 v[22:23], v[22:23], 0, s[42:43]
	v_add_u32_e32 v26, v30, v142
	v_add_u32_e32 v51, 0x1c0, v1
	v_addc_co_u32_e32 v19, vcc, 0, v19, vcc
	v_lshl_add_u64 v[22:23], v[22:23], 0, v[182:183]
	v_mad_i64_i32 v[26:27], s[4:5], v26, s33, v[88:89]
	v_ashrrev_i32_e32 v143, 4, v51
	v_add_co_u32_e32 v22, vcc, s25, v22
	v_lshl_add_u64 v[26:27], v[26:27], 0, s[42:43]
	v_add_u32_e32 v30, v30, v143
	v_addc_co_u32_e32 v23, vcc, 0, v23, vcc
	v_lshl_add_u64 v[26:27], v[26:27], 0, v[182:183]
	v_mad_i64_i32 v[30:31], s[4:5], v30, s33, v[88:89]
	v_add_co_u32_e32 v26, vcc, s25, v26
	v_lshl_add_u64 v[30:31], v[30:31], 0, s[42:43]
	s_nop 0
	v_addc_co_u32_e32 v27, vcc, 0, v27, vcc
	v_lshl_add_u64 v[30:31], v[30:31], 0, v[182:183]
	v_add_co_u32_e32 v30, vcc, s25, v30
	global_load_dwordx4 v[6:9], v[6:7], off
	s_nop 0
	v_addc_co_u32_e32 v31, vcc, 0, v31, vcc
	global_load_dwordx4 v[10:13], v[10:11], off
	v_lshlrev_b32_e32 v42, 1, v91
	global_load_dwordx4 v[14:17], v[14:15], off
	v_bfe_u32 v52, v1, 4, 2
	global_load_dwordx4 v[18:21], v[18:19], off
	v_and_or_b32 v42, v42, 28, v52
	global_load_dwordx4 v[22:25], v[22:23], off
	v_lshlrev_b32_e32 v52, 4, v91
	global_load_dwordx4 v[26:29], v[26:27], off
	v_lshlrev_b32_e32 v42, 5, v42
	global_load_dwordx4 v[30:33], v[30:31], off
	v_and_b32_e32 v52, 16, v52
	v_lshlrev_b32_e32 v44, 3, v1
	v_add3_u32 v42, s47, v52, v42
	v_or_b32_e32 v144, 64, v43
	v_mul_lo_u32 v43, v71, s94
	v_lshlrev_b32_e32 v52, 3, v91
	v_add_u32_e32 v43, s47, v43
	v_and_b32_e32 v52, 0x60, v52
	v_and_b32_e32 v44, 24, v44
	v_add3_u32 v119, v43, v52, v44
	v_lshrrev_b32_e32 v43, 6, v1
	v_mad_u64_u32 v[72:73], s[4:5], v43, s94, v[42:43]
	v_cvt_pk_bf16_f32 v62, v34, v35
	v_cvt_pk_bf16_f32 v63, v36, v37
	v_cvt_pk_bf16_f32 v64, v38, v39
	v_cvt_pk_bf16_f32 v65, v40, v41
	v_cvt_pk_bf16_f32 v120, v120, v121
	v_cvt_pk_bf16_f32 v121, v122, v123
	v_cvt_pk_bf16_f32 v122, v124, v125
	v_cvt_pk_bf16_f32 v123, v126, v127
	ds_bpermute_b32 v100, v96, v99
	s_waitcnt vmcnt(7)
; #define LAS __attribute__((address_space(3)))
; __device__ __forceinline__ unsigned pk2(float lo, float hi) { const f32x2 v = {lo, hi}; return __builtin_bit_cast(unsigned, __builtin_convertvector(v, bf16x2_t)); }
; __device__ __forceinline__ s16x4 tr16(const LAS unsigned char* p) { return __builtin_bit_cast(s16x4, __builtin_amdgcn_ds_read_tr16_b64_v4i16((LAS s16x4*)p)); }
; __device__ __forceinline__ bf16x8 cat8(s16x4 lo, s16x4 hi) { return __builtin_shufflevector(lo, hi, 0, 1, 2, 3, 4, 5, 6, 7); }
; __device__ __forceinline__ f32x4 mfma16(bf16x8 a, bf16x8 b, f32x4 c) { return __builtin_amdgcn_mfma_f32_16x16x32_bf16(a, b, c, 0, 0, 0); }
; #define LDS_WAIT() asm volatile("s_waitcnt lgkmcnt(0)" ::: "memory")
; __device__ __forceinline__ int trw_off(int row, int c8  , int GP) { return (row >> 2) * GP + (((c8 >> 1) * 4 + (row & 3)) * 32) + (c8 & 1) * 16; }
; __device__ __forceinline__ void attn_phase(const bf16* proj, bf16* mixed, const float* rpb, const float* gain_a, LAS unsigned char* lds, int vb, int nb, int wave, int lane_in) {
;     ...
;         for (int w = 0; w < 8; ++w) {
; #pragma unroll
;             for (int i = 0; i < 8; ++i) { const int id = lane + 64 * i, j = id >> 4, ch = id & 15; *(LAS v4u*)(vt + trw_off(j, ch, 1152)) = vr[i]; }
;             if (w < 7) { const int vtok0 = base + 64 * (row_start + w + 1) + blk_start;
; #pragma unroll
;                 for (int i = 0; i < 8; ++i) { const int id = lane + 64 * i, j = id >> 4, ch = id & 15; vr[i] = *(const v4u*)(proj + (size_t)(vtok0 + j) * NIN + C_AV + h * 128 + ch * 8); } }
;             LDS_WAIT();
;             bf16x8 pb;
;             { v4u pw; pw.x = pk2(sc[2 * w][0], sc[2 * w][1]); pw.y = pk2(sc[2 * w][2], sc[2 * w][3]); pw.z = pk2(sc[2 * w + 1][0], sc[2 * w + 1][1]); pw.w = pk2(sc[2 * w + 1][2], sc[2 * w + 1][3]); pb = __builtin_bit_cast(bf16x8, pw); }
;             const LAS unsigned char* tb = vt + g * 1152 + (qi >> 2) * 32 + (qi & 3) * 8;
; #pragma unroll
;             for (int v = 0; v < 8; ++v) {
;                 const s16x4 lo = tr16(tb + v * 128), hi = tr16(tb + 4 * 1152 + v * 128);
;                 o[v] = mfma16(cat8(lo, hi), pb, o[v]);
;             }
	ds_write_b128 v72, v[2:5]
	v_lshrrev_b32_e32 v2, 6, v45
	v_mad_u64_u32 v[74:75], s[4:5], v2, s94, v[42:43]
	v_lshrrev_b32_e32 v2, 6, v46
	v_mad_u64_u32 v[76:77], s[4:5], v2, s94, v[42:43]
	v_lshrrev_b32_e32 v2, 6, v47
	v_mad_u64_u32 v[78:79], s[4:5], v2, s94, v[42:43]
	v_lshrrev_b32_e32 v2, 6, v48
	v_mad_u64_u32 v[80:81], s[4:5], v2, s94, v[42:43]
	v_lshrrev_b32_e32 v2, 6, v49
	v_mad_u64_u32 v[82:83], s[4:5], v2, s94, v[42:43]
	v_lshrrev_b32_e32 v2, 6, v50
	v_mad_u64_u32 v[84:85], s[4:5], v2, s94, v[42:43]
	v_lshrrev_b32_e32 v2, 6, v51
	v_mad_u64_u32 v[86:87], s[4:5], v2, s94, v[42:43]
	s_waitcnt vmcnt(6)
	ds_write_b128 v74, v[6:9]
	s_waitcnt vmcnt(5)
	ds_write_b128 v76, v[10:13]
	s_waitcnt vmcnt(4)
	ds_write_b128 v78, v[14:17]
	s_waitcnt vmcnt(3)
	ds_write_b128 v80, v[18:21]
	s_waitcnt vmcnt(2)
	ds_write_b128 v82, v[22:25]
	s_waitcnt vmcnt(1)
	ds_write_b128 v84, v[26:29]
	s_waitcnt vmcnt(0)
	ds_write_b128 v86, v[30:33]
	v_add_u32_e32 v30, v128, v144
	v_add_u32_e32 v2, v30, v143
	v_mad_i64_i32 v[2:3], s[4:5], v2, s33, v[88:89]
	v_lshl_add_u64 v[2:3], v[2:3], 0, s[42:43]
	v_add_u32_e32 v6, v30, v142
	v_lshl_add_u64 v[2:3], v[2:3], 0, v[182:183]
	v_mad_i64_i32 v[6:7], s[4:5], v6, s33, v[88:89]
	v_add_co_u32_e32 v2, vcc, s25, v2
	v_lshl_add_u64 v[6:7], v[6:7], 0, s[42:43]
	v_add_u32_e32 v10, v30, v141
	v_addc_co_u32_e32 v3, vcc, 0, v3, vcc
	v_lshl_add_u64 v[6:7], v[6:7], 0, v[182:183]
	v_mad_i64_i32 v[10:11], s[4:5], v10, s33, v[88:89]
	v_add_co_u32_e32 v6, vcc, s25, v6
	v_lshl_add_u64 v[10:11], v[10:11], 0, s[42:43]
	v_add_u32_e32 v14, v30, v140
	v_addc_co_u32_e32 v7, vcc, 0, v7, vcc
	v_lshl_add_u64 v[10:11], v[10:11], 0, v[182:183]
	v_mad_i64_i32 v[14:15], s[4:5], v14, s33, v[88:89]
	v_add_co_u32_e32 v10, vcc, s25, v10
	v_lshl_add_u64 v[14:15], v[14:15], 0, s[42:43]
	v_add_u32_e32 v18, v30, v139
	v_addc_co_u32_e32 v11, vcc, 0, v11, vcc
	v_lshl_add_u64 v[14:15], v[14:15], 0, v[182:183]
	v_mad_i64_i32 v[18:19], s[4:5], v18, s33, v[88:89]
	v_add_co_u32_e32 v14, vcc, s25, v14
	v_lshl_add_u64 v[18:19], v[18:19], 0, s[42:43]
	v_add_u32_e32 v22, v30, v138
	v_addc_co_u32_e32 v15, vcc, 0, v15, vcc
	v_lshl_add_u64 v[18:19], v[18:19], 0, v[182:183]
	v_mad_i64_i32 v[22:23], s[4:5], v22, s33, v[88:89]
	v_add_co_u32_e32 v18, vcc, s25, v18
	v_lshl_add_u64 v[22:23], v[22:23], 0, s[42:43]
	v_add_u32_e32 v26, v30, v137
	v_addc_co_u32_e32 v19, vcc, 0, v19, vcc
	v_lshl_add_u64 v[22:23], v[22:23], 0, v[182:183]
	v_mad_i64_i32 v[26:27], s[4:5], v26, s33, v[88:89]
	v_add_co_u32_e32 v22, vcc, s25, v22
	v_lshl_add_u64 v[26:27], v[26:27], 0, s[42:43]
	v_add_u32_e32 v30, v30, v71
	v_addc_co_u32_e32 v23, vcc, 0, v23, vcc
	v_lshl_add_u64 v[26:27], v[26:27], 0, v[182:183]
	v_mad_i64_i32 v[30:31], s[4:5], v30, s33, v[88:89]
	v_add_co_u32_e32 v26, vcc, s25, v26
	v_lshl_add_u64 v[30:31], v[30:31], 0, s[42:43]
	s_nop 0
	v_addc_co_u32_e32 v27, vcc, 0, v27, vcc
	v_lshl_add_u64 v[30:31], v[30:31], 0, v[182:183]
	v_add_co_u32_e32 v30, vcc, s25, v30
	global_load_dwordx4 v[26:29], v[26:27], off
	s_nop 0
	v_addc_co_u32_e32 v31, vcc, 0, v31, vcc
	global_load_dwordx4 v[30:33], v[30:31], off
	v_cvt_pk_bf16_f32 v128, v129, v130
	global_load_dwordx4 v[18:21], v[18:19], off
	v_cvt_pk_bf16_f32 v129, v131, v132
	global_load_dwordx4 v[22:25], v[22:23], off
	v_cvt_pk_bf16_f32 v130, v133, v134
	global_load_dwordx4 v[10:13], v[10:11], off
	v_cvt_pk_bf16_f32 v131, v135, v136
	global_load_dwordx4 v[14:17], v[14:15], off
	s_nop 0
	global_load_dwordx4 v[2:5], v[2:3], off
	s_nop 0
	global_load_dwordx4 v[6:9], v[6:7], off
	s_waitcnt lgkmcnt(0)
	ds_read_b64_tr_b16 v[34:35], v119
	ds_read_b64_tr_b16 v[36:37], v119 offset:4608
	s_waitcnt lgkmcnt(0)
	v_mfma_f32_16x16x32_bf16 v[46:49], v[34:37], v[62:65], 0
	ds_read_b64_tr_b16 v[34:35], v119 offset:128
	ds_read_b64_tr_b16 v[36:37], v119 offset:4736
	ds_read_b64_tr_b16 v[38:39], v119 offset:256
	ds_read_b64_tr_b16 v[40:41], v119 offset:4864
	ds_read_b64_tr_b16 v[42:43], v119 offset:384
	ds_read_b64_tr_b16 v[44:45], v119 offset:4992
	ds_read_b64_tr_b16 v[50:51], v119 offset:512
	ds_read_b64_tr_b16 v[52:53], v119 offset:5120
	ds_read_b64_tr_b16 v[54:55], v119 offset:640
	ds_read_b64_tr_b16 v[56:57], v119 offset:5248
	ds_read_b64_tr_b16 v[58:59], v119 offset:768
	ds_read_b64_tr_b16 v[60:61], v119 offset:5376
	ds_read_b64_tr_b16 v[66:67], v119 offset:896
	ds_read_b64_tr_b16 v[68:69], v119 offset:5504
	s_waitcnt lgkmcnt(0)
	s_waitcnt vmcnt(6)
	ds_write_b128 v72, v[30:33]
	ds_write_b128 v74, v[26:29]
	s_waitcnt vmcnt(4)
	ds_write_b128 v76, v[22:25]
	ds_write_b128 v78, v[18:21]
	s_waitcnt vmcnt(2)
	ds_write_b128 v80, v[14:17]
	ds_write_b128 v82, v[10:13]
	s_waitcnt vmcnt(0)
	ds_write_b128 v84, v[6:9]
	ds_write_b128 v86, v[2:5]
	v_add_u32_e32 v4, v118, v144
	v_add_u32_e32 v2, v4, v143
	v_mad_i64_i32 v[2:3], s[4:5], v2, s33, v[88:89]
	v_lshl_add_u64 v[2:3], v[2:3], 0, s[42:43]
	v_lshl_add_u64 v[2:3], v[2:3], 0, v[182:183]
	v_add_co_u32_e32 v2, vcc, s25, v2
	s_waitcnt lgkmcnt(14)
	v_mfma_f32_16x16x32_bf16 v[34:37], v[34:37], v[62:65], 0
	v_addc_co_u32_e32 v3, vcc, 0, v3, vcc
	global_load_dwordx4 v[14:17], v[2:3], off
	v_add_u32_e32 v2, v4, v142
	v_mad_i64_i32 v[2:3], s[4:5], v2, s33, v[88:89]
	v_lshl_add_u64 v[2:3], v[2:3], 0, s[42:43]
	v_lshl_add_u64 v[2:3], v[2:3], 0, v[182:183]
	v_add_co_u32_e32 v2, vcc, s25, v2
	v_mfma_f32_16x16x32_bf16 v[38:41], v[38:41], v[62:65], 0
	s_nop 0
	v_addc_co_u32_e32 v3, vcc, 0, v3, vcc
	v_cvt_pk_bf16_f32 v5, v168, v169
	v_mfma_f32_16x16x32_bf16 v[42:45], v[42:45], v[62:65], 0
	v_mfma_f32_16x16x32_bf16 v[50:53], v[50:53], v[62:65], 0
	s_waitcnt lgkmcnt(12)
	v_mfma_f32_16x16x32_bf16 v[54:57], v[54:57], v[62:65], 0
	s_waitcnt lgkmcnt(10)
; #define LAS __attribute__((address_space(3)))
; __device__ __forceinline__ unsigned pk2(float lo, float hi) { const f32x2 v = {lo, hi}; return __builtin_bit_cast(unsigned, __builtin_convertvector(v, bf16x2_t)); }
; __device__ __forceinline__ s16x4 tr16(const LAS unsigned char* p) { return __builtin_bit_cast(s16x4, __builtin_amdgcn_ds_read_tr16_b64_v4i16((LAS s16x4*)p)); }
; __device__ __forceinline__ bf16x8 cat8(s16x4 lo, s16x4 hi) { return __builtin_shufflevector(lo, hi, 0, 1, 2, 3, 4, 5, 6, 7); }
; __device__ __forceinline__ f32x4 mfma16(bf16x8 a, bf16x8 b, f32x4 c) { return __builtin_amdgcn_mfma_f32_16x16x32_bf16(a, b, c, 0, 0, 0); }
; #define LDS_WAIT() asm volatile("s_waitcnt lgkmcnt(0)" ::: "memory")
; __device__ __forceinline__ void attn_phase(const bf16* proj, bf16* mixed, const float* rpb, const float* gain_a, LAS unsigned char* lds, int vb, int nb, int wave, int lane_in) {
;     ...
;         { const int vtok0 = base + 64 * row_start + blk_start;
; #pragma unroll
;           for (int i = 0; i < 8; ++i) { const int id = lane + 64 * i, j = id >> 4, ch = id & 15; vr[i] = *(const v4u*)(proj + (size_t)(vtok0 + j) * NIN + C_AV + h * 128 + ch * 8); } }
; #pragma unroll
;         for (int w = 0; w < 8; ++w) {
; #pragma unroll
;             for (int i = 0; i < 8; ++i) { const int id = lane + 64 * i, j = id >> 4, ch = id & 15; *(LAS v4u*)(vt + trw_off(j, ch, 1152)) = vr[i]; }
;             if (w < 7) { const int vtok0 = base + 64 * (row_start + w + 1) + blk_start;
; #pragma unroll
;                 for (int i = 0; i < 8; ++i) { const int id = lane + 64 * i, j = id >> 4, ch = id & 15; vr[i] = *(const v4u*)(proj + (size_t)(vtok0 + j) * NIN + C_AV + h * 128 + ch * 8); } }
;             LDS_WAIT();
;             bf16x8 pb;
;             { v4u pw; pw.x = pk2(sc[2 * w][0], sc[2 * w][1]); pw.y = pk2(sc[2 * w][2], sc[2 * w][3]); pw.z = pk2(sc[2 * w + 1][0], sc[2 * w + 1][1]); pw.w = pk2(sc[2 * w + 1][2], sc[2 * w + 1][3]); pb = __builtin_bit_cast(bf16x8, pw); }
;             const LAS unsigned char* tb = vt + g * 1152 + (qi >> 2) * 32 + (qi & 3) * 8;
; #pragma unroll
;             for (int v = 0; v < 8; ++v) {
;                 const s16x4 lo = tr16(tb + v * 128), hi = tr16(tb + 4 * 1152 + v * 128);
;                 o[v] = mfma16(cat8(lo, hi), pb, o[v]);
;             }
;             LDS_WAIT();
	v_mfma_f32_16x16x32_bf16 v[58:61], v[58:61], v[62:65], 0
	s_waitcnt lgkmcnt(8)
	v_mfma_f32_16x16x32_bf16 v[62:65], v[66:69], v[62:65], 0
	global_load_dwordx4 v[66:69], v[2:3], off
	v_add_u32_e32 v2, v4, v141
	v_mad_i64_i32 v[2:3], s[4:5], v2, s33, v[88:89]
	v_lshl_add_u64 v[2:3], v[2:3], 0, s[42:43]
	v_lshl_add_u64 v[2:3], v[2:3], 0, v[182:183]
	v_add_co_u32_e32 v2, vcc, s25, v2
	s_nop 1
	v_addc_co_u32_e32 v3, vcc, 0, v3, vcc
	global_load_dwordx4 v[170:173], v[2:3], off
	v_add_u32_e32 v2, v4, v140
	v_mad_i64_i32 v[2:3], s[4:5], v2, s33, v[88:89]
	v_lshl_add_u64 v[2:3], v[2:3], 0, s[42:43]
	v_lshl_add_u64 v[2:3], v[2:3], 0, v[182:183]
	v_add_co_u32_e32 v2, vcc, s25, v2
	s_nop 1
	v_addc_co_u32_e32 v3, vcc, 0, v3, vcc
	global_load_dwordx4 v[174:177], v[2:3], off
	v_add_u32_e32 v2, v4, v139
	v_mad_i64_i32 v[2:3], s[4:5], v2, s33, v[88:89]
	v_lshl_add_u64 v[2:3], v[2:3], 0, s[42:43]
	v_lshl_add_u64 v[2:3], v[2:3], 0, v[182:183]
	v_add_co_u32_e32 v2, vcc, s25, v2
	s_nop 1
	v_addc_co_u32_e32 v3, vcc, 0, v3, vcc
	global_load_dwordx4 v[178:181], v[2:3], off
	v_add_u32_e32 v2, v4, v138
	v_mad_i64_i32 v[2:3], s[4:5], v2, s33, v[88:89]
	v_lshl_add_u64 v[2:3], v[2:3], 0, s[42:43]
	v_lshl_add_u64 v[2:3], v[2:3], 0, v[182:183]
	v_add_co_u32_e32 v2, vcc, s25, v2
	s_nop 1
	v_addc_co_u32_e32 v3, vcc, 0, v3, vcc
	global_load_dwordx4 v[198:201], v[2:3], off
	v_add_u32_e32 v2, v4, v137
	v_mad_i64_i32 v[2:3], s[4:5], v2, s33, v[88:89]
	v_lshl_add_u64 v[2:3], v[2:3], 0, s[42:43]
	v_lshl_add_u64 v[2:3], v[2:3], 0, v[182:183]
	v_add_co_u32_e32 v2, vcc, s25, v2
	s_nop 1
	v_addc_co_u32_e32 v3, vcc, 0, v3, vcc
	global_load_dwordx4 v[202:205], v[2:3], off
	v_add_u32_e32 v2, v4, v71
	v_mad_i64_i32 v[2:3], s[4:5], v2, s33, v[88:89]
	v_lshl_add_u64 v[2:3], v[2:3], 0, s[42:43]
	v_lshl_add_u64 v[2:3], v[2:3], 0, v[182:183]
	v_add_co_u32_e32 v2, vcc, s25, v2
	v_cvt_pk_bf16_f32 v4, v166, v167
	s_nop 0
	v_addc_co_u32_e32 v3, vcc, 0, v3, vcc
	global_load_dwordx4 v[206:209], v[2:3], off
	s_waitcnt lgkmcnt(0)
	ds_read_b64_tr_b16 v[6:7], v119
	ds_read_b64_tr_b16 v[8:9], v119 offset:4608
	v_cvt_pk_bf16_f32 v2, v162, v163
	v_cvt_pk_bf16_f32 v3, v164, v165
	s_waitcnt lgkmcnt(0)
	s_nop 0
	v_mfma_f32_16x16x32_bf16 v[22:25], v[6:9], v[2:5], v[46:49]
	ds_read_b64_tr_b16 v[6:7], v119 offset:128
	ds_read_b64_tr_b16 v[8:9], v119 offset:4736
	s_waitcnt lgkmcnt(0)
	v_mfma_f32_16x16x32_bf16 v[34:37], v[6:9], v[2:5], v[34:37]
	ds_read_b64_tr_b16 v[6:7], v119 offset:256
	ds_read_b64_tr_b16 v[8:9], v119 offset:4864
	s_waitcnt lgkmcnt(0)
	v_mfma_f32_16x16x32_bf16 v[30:33], v[6:9], v[2:5], v[38:41]
	ds_read_b64_tr_b16 v[6:7], v119 offset:384
	ds_read_b64_tr_b16 v[8:9], v119 offset:4992
	s_waitcnt lgkmcnt(0)
	v_mfma_f32_16x16x32_bf16 v[26:29], v[6:9], v[2:5], v[42:45]
	ds_read_b64_tr_b16 v[6:7], v119 offset:512
	ds_read_b64_tr_b16 v[8:9], v119 offset:5120
	s_waitcnt lgkmcnt(0)
	v_mfma_f32_16x16x32_bf16 v[18:21], v[6:9], v[2:5], v[50:53]
	ds_read_b64_tr_b16 v[6:7], v119 offset:640
	ds_read_b64_tr_b16 v[8:9], v119 offset:5248
	s_waitcnt lgkmcnt(0)
	v_mfma_f32_16x16x32_bf16 v[10:13], v[6:9], v[2:5], v[54:57]
	ds_read_b64_tr_b16 v[6:7], v119 offset:768
	ds_read_b64_tr_b16 v[8:9], v119 offset:5376
	ds_read_b64_tr_b16 v[38:39], v119 offset:896
	ds_read_b64_tr_b16 v[40:41], v119 offset:5504
	s_waitcnt lgkmcnt(0)
	s_waitcnt lgkmcnt(2)
	v_mfma_f32_16x16x32_bf16 v[6:9], v[6:9], v[2:5], v[58:61]
	s_waitcnt vmcnt(0)
	ds_write_b128 v72, v[206:209]
	ds_write_b128 v74, v[202:205]
	ds_write_b128 v76, v[198:201]
	ds_write_b128 v78, v[178:181]
	ds_write_b128 v80, v[174:177]
	ds_write_b128 v82, v[170:173]
	ds_write_b128 v84, v[66:69]
	ds_write_b128 v86, v[14:17]
	s_waitcnt lgkmcnt(8)
	v_mfma_f32_16x16x32_bf16 v[2:5], v[38:41], v[2:5], v[62:65]
	v_cvt_pk_bf16_f32 v66, v154, v155
	v_cvt_pk_bf16_f32 v67, v156, v157
	v_cvt_pk_bf16_f32 v68, v158, v159
	v_add_u32_e32 v62, v109, v144
	v_add_u32_e32 v14, v62, v143
	v_mad_i64_i32 v[14:15], s[4:5], v14, s33, v[88:89]
	v_lshl_add_u64 v[14:15], v[14:15], 0, s[42:43]
	v_add_u32_e32 v38, v62, v142
	v_lshl_add_u64 v[14:15], v[14:15], 0, v[182:183]
	v_mad_i64_i32 v[38:39], s[4:5], v38, s33, v[88:89]
	v_add_co_u32_e32 v14, vcc, s25, v14
	v_lshl_add_u64 v[38:39], v[38:39], 0, s[42:43]
	v_add_u32_e32 v42, v62, v141
	v_addc_co_u32_e32 v15, vcc, 0, v15, vcc
	v_lshl_add_u64 v[38:39], v[38:39], 0, v[182:183]
	v_mad_i64_i32 v[42:43], s[4:5], v42, s33, v[88:89]
	v_add_co_u32_e32 v38, vcc, s25, v38
	v_lshl_add_u64 v[42:43], v[42:43], 0, s[42:43]
	v_add_u32_e32 v46, v62, v140
	v_addc_co_u32_e32 v39, vcc, 0, v39, vcc
	v_lshl_add_u64 v[42:43], v[42:43], 0, v[182:183]
	v_mad_i64_i32 v[46:47], s[4:5], v46, s33, v[88:89]
	v_add_co_u32_e32 v42, vcc, s25, v42
	v_lshl_add_u64 v[46:47], v[46:47], 0, s[42:43]
	v_add_u32_e32 v50, v62, v139
	v_addc_co_u32_e32 v43, vcc, 0, v43, vcc
	v_lshl_add_u64 v[46:47], v[46:47], 0, v[182:183]
	v_mad_i64_i32 v[50:51], s[4:5], v50, s33, v[88:89]
	v_add_co_u32_e32 v46, vcc, s25, v46
	v_lshl_add_u64 v[50:51], v[50:51], 0, s[42:43]
	v_add_u32_e32 v54, v62, v138
	v_addc_co_u32_e32 v47, vcc, 0, v47, vcc
	v_lshl_add_u64 v[50:51], v[50:51], 0, v[182:183]
	v_mad_i64_i32 v[54:55], s[4:5], v54, s33, v[88:89]
	v_add_co_u32_e32 v50, vcc, s25, v50
	v_lshl_add_u64 v[54:55], v[54:55], 0, s[42:43]
	v_add_u32_e32 v58, v62, v137
	v_addc_co_u32_e32 v51, vcc, 0, v51, vcc
	v_lshl_add_u64 v[54:55], v[54:55], 0, v[182:183]
	v_mad_i64_i32 v[58:59], s[4:5], v58, s33, v[88:89]
	v_add_co_u32_e32 v54, vcc, s25, v54
	v_lshl_add_u64 v[58:59], v[58:59], 0, s[42:43]
	v_add_u32_e32 v62, v62, v71
	v_addc_co_u32_e32 v55, vcc, 0, v55, vcc
	v_lshl_add_u64 v[58:59], v[58:59], 0, v[182:183]
	v_mad_i64_i32 v[62:63], s[4:5], v62, s33, v[88:89]
	v_add_co_u32_e32 v58, vcc, s25, v58
	v_lshl_add_u64 v[62:63], v[62:63], 0, s[42:43]
	s_nop 0
	v_addc_co_u32_e32 v59, vcc, 0, v59, vcc
	v_lshl_add_u64 v[62:63], v[62:63], 0, v[182:183]
	v_add_co_u32_e32 v62, vcc, s25, v62
	global_load_dwordx4 v[58:61], v[58:59], off
	s_nop 0
	v_addc_co_u32_e32 v63, vcc, 0, v63, vcc
	global_load_dwordx4 v[62:65], v[62:63], off
	v_cvt_pk_bf16_f32 v69, v160, v161
	global_load_dwordx4 v[50:53], v[50:51], off
	s_nop 0
	global_load_dwordx4 v[54:57], v[54:55], off
	s_nop 0
	global_load_dwordx4 v[42:45], v[42:43], off
	s_nop 0
	global_load_dwordx4 v[46:49], v[46:47], off
	s_nop 0
	global_load_dwordx4 v[14:17], v[14:15], off
	s_nop 0
	global_load_dwordx4 v[38:41], v[38:39], off
	s_waitcnt lgkmcnt(0)
; #define LAS __attribute__((address_space(3)))
; __device__ __forceinline__ unsigned pk2(float lo, float hi) { const f32x2 v = {lo, hi}; return __builtin_bit_cast(unsigned, __builtin_convertvector(v, bf16x2_t)); }
; __device__ __forceinline__ s16x4 tr16(const LAS unsigned char* p) { return __builtin_bit_cast(s16x4, __builtin_amdgcn_ds_read_tr16_b64_v4i16((LAS s16x4*)p)); }
; __device__ __forceinline__ bf16x8 cat8(s16x4 lo, s16x4 hi) { return __builtin_shufflevector(lo, hi, 0, 1, 2, 3, 4, 5, 6, 7); }
; __device__ __forceinline__ f32x4 mfma16(bf16x8 a, bf16x8 b, f32x4 c) { return __builtin_amdgcn_mfma_f32_16x16x32_bf16(a, b, c, 0, 0, 0); }
; #define LDS_WAIT() asm volatile("s_waitcnt lgkmcnt(0)" ::: "memory")
; __device__ __forceinline__ int trw_off(int row, int c8  , int GP) { return (row >> 2) * GP + (((c8 >> 1) * 4 + (row & 3)) * 32) + (c8 & 1) * 16; }
; __device__ __forceinline__ void attn_phase(const bf16* proj, bf16* mixed, const float* rpb, const float* gain_a, LAS unsigned char* lds, int vb, int nb, int wave, int lane_in) {
;     ...
;         for (int w = 0; w < 8; ++w) {
; #pragma unroll
;             for (int i = 0; i < 8; ++i) { const int id = lane + 64 * i, j = id >> 4, ch = id & 15; *(LAS v4u*)(vt + trw_off(j, ch, 1152)) = vr[i]; }
;             if (w < 7) { const int vtok0 = base + 64 * (row_start + w + 1) + blk_start;
; #pragma unroll
;                 for (int i = 0; i < 8; ++i) { const int id = lane + 64 * i, j = id >> 4, ch = id & 15; vr[i] = *(const v4u*)(proj + (size_t)(vtok0 + j) * NIN + C_AV + h * 128 + ch * 8); } }
;             LDS_WAIT();
;             bf16x8 pb;
;             { v4u pw; pw.x = pk2(sc[2 * w][0], sc[2 * w][1]); pw.y = pk2(sc[2 * w][2], sc[2 * w][3]); pw.z = pk2(sc[2 * w + 1][0], sc[2 * w + 1][1]); pw.w = pk2(sc[2 * w + 1][2], sc[2 * w + 1][3]); pb = __builtin_bit_cast(bf16x8, pw); }
;             const LAS unsigned char* tb = vt + g * 1152 + (qi >> 2) * 32 + (qi & 3) * 8;
; #pragma unroll
;             for (int v = 0; v < 8; ++v) {
;                 const s16x4 lo = tr16(tb + v * 128), hi = tr16(tb + 4 * 1152 + v * 128);
;                 o[v] = mfma16(cat8(lo, hi), pb, o[v]);
;             }
;             LDS_WAIT();
	ds_read_b64_tr_b16 v[154:155], v119
	ds_read_b64_tr_b16 v[156:157], v119 offset:4608
	s_waitcnt lgkmcnt(0)
	v_mfma_f32_16x16x32_bf16 v[22:25], v[154:157], v[66:69], v[22:25]
	ds_read_b64_tr_b16 v[154:155], v119 offset:128
	ds_read_b64_tr_b16 v[156:157], v119 offset:4736
	s_waitcnt lgkmcnt(0)
	v_mfma_f32_16x16x32_bf16 v[34:37], v[154:157], v[66:69], v[34:37]
	ds_read_b64_tr_b16 v[154:155], v119 offset:256
	ds_read_b64_tr_b16 v[156:157], v119 offset:4864
	s_waitcnt lgkmcnt(0)
	v_mfma_f32_16x16x32_bf16 v[30:33], v[154:157], v[66:69], v[30:33]
	ds_read_b64_tr_b16 v[154:155], v119 offset:384
	ds_read_b64_tr_b16 v[156:157], v119 offset:4992
	s_waitcnt lgkmcnt(0)
	v_mfma_f32_16x16x32_bf16 v[26:29], v[154:157], v[66:69], v[26:29]
	ds_read_b64_tr_b16 v[154:155], v119 offset:512
	ds_read_b64_tr_b16 v[156:157], v119 offset:5120
	s_waitcnt lgkmcnt(0)
	v_mfma_f32_16x16x32_bf16 v[18:21], v[154:157], v[66:69], v[18:21]
	ds_read_b64_tr_b16 v[154:155], v119 offset:640
	ds_read_b64_tr_b16 v[156:157], v119 offset:5248
	s_waitcnt lgkmcnt(0)
	v_mfma_f32_16x16x32_bf16 v[10:13], v[154:157], v[66:69], v[10:13]
	ds_read_b64_tr_b16 v[154:155], v119 offset:768
	ds_read_b64_tr_b16 v[156:157], v119 offset:5376
	s_waitcnt lgkmcnt(0)
	v_mfma_f32_16x16x32_bf16 v[6:9], v[154:157], v[66:69], v[6:9]
	ds_read_b64_tr_b16 v[154:155], v119 offset:896
	ds_read_b64_tr_b16 v[156:157], v119 offset:5504
	s_waitcnt lgkmcnt(0)
	s_waitcnt vmcnt(6)
	ds_write_b128 v72, v[62:65]
	ds_write_b128 v74, v[58:61]
	s_waitcnt vmcnt(4)
	ds_write_b128 v76, v[54:57]
	ds_write_b128 v78, v[50:53]
	s_waitcnt vmcnt(2)
	ds_write_b128 v80, v[46:49]
	ds_write_b128 v82, v[42:45]
	s_waitcnt vmcnt(0)
	ds_write_b128 v84, v[38:41]
	ds_write_b128 v86, v[14:17]
	v_add_u32_e32 v62, v98, v144
	v_add_u32_e32 v14, v62, v143
	v_mad_i64_i32 v[14:15], s[4:5], v14, s33, v[88:89]
	v_lshl_add_u64 v[14:15], v[14:15], 0, s[42:43]
	v_add_u32_e32 v38, v62, v142
	v_lshl_add_u64 v[14:15], v[14:15], 0, v[182:183]
	v_mad_i64_i32 v[38:39], s[4:5], v38, s33, v[88:89]
	v_add_co_u32_e32 v14, vcc, s25, v14
	v_lshl_add_u64 v[38:39], v[38:39], 0, s[42:43]
	v_add_u32_e32 v42, v62, v141
	v_addc_co_u32_e32 v15, vcc, 0, v15, vcc
	v_lshl_add_u64 v[38:39], v[38:39], 0, v[182:183]
	v_mad_i64_i32 v[42:43], s[4:5], v42, s33, v[88:89]
	v_add_co_u32_e32 v38, vcc, s25, v38
	v_lshl_add_u64 v[42:43], v[42:43], 0, s[42:43]
	v_add_u32_e32 v46, v62, v140
	v_addc_co_u32_e32 v39, vcc, 0, v39, vcc
	v_lshl_add_u64 v[42:43], v[42:43], 0, v[182:183]
	v_mad_i64_i32 v[46:47], s[4:5], v46, s33, v[88:89]
	v_add_co_u32_e32 v42, vcc, s25, v42
	v_lshl_add_u64 v[46:47], v[46:47], 0, s[42:43]
	v_add_u32_e32 v50, v62, v139
	v_addc_co_u32_e32 v43, vcc, 0, v43, vcc
	v_lshl_add_u64 v[46:47], v[46:47], 0, v[182:183]
	v_mad_i64_i32 v[50:51], s[4:5], v50, s33, v[88:89]
	v_add_co_u32_e32 v46, vcc, s25, v46
	v_lshl_add_u64 v[50:51], v[50:51], 0, s[42:43]
	v_add_u32_e32 v54, v62, v138
	v_addc_co_u32_e32 v47, vcc, 0, v47, vcc
	v_lshl_add_u64 v[50:51], v[50:51], 0, v[182:183]
	v_mad_i64_i32 v[54:55], s[4:5], v54, s33, v[88:89]
	v_add_co_u32_e32 v50, vcc, s25, v50
	v_lshl_add_u64 v[54:55], v[54:55], 0, s[42:43]
	v_add_u32_e32 v58, v62, v137
	v_addc_co_u32_e32 v51, vcc, 0, v51, vcc
	v_lshl_add_u64 v[54:55], v[54:55], 0, v[182:183]
	v_mad_i64_i32 v[58:59], s[4:5], v58, s33, v[88:89]
	v_add_co_u32_e32 v54, vcc, s25, v54
	v_lshl_add_u64 v[58:59], v[58:59], 0, s[42:43]
	v_add_u32_e32 v62, v62, v71
	v_addc_co_u32_e32 v55, vcc, 0, v55, vcc
	v_lshl_add_u64 v[58:59], v[58:59], 0, v[182:183]
	v_mad_i64_i32 v[62:63], s[4:5], v62, s33, v[88:89]
	v_add_co_u32_e32 v58, vcc, s25, v58
	v_lshl_add_u64 v[62:63], v[62:63], 0, s[42:43]
	s_nop 0
	v_addc_co_u32_e32 v59, vcc, 0, v59, vcc
	v_lshl_add_u64 v[62:63], v[62:63], 0, v[182:183]
	v_add_co_u32_e32 v62, vcc, s25, v62
	global_load_dwordx4 v[58:61], v[58:59], off
	s_nop 0
	v_addc_co_u32_e32 v63, vcc, 0, v63, vcc
	global_load_dwordx4 v[62:65], v[62:63], off
	s_waitcnt lgkmcnt(8)
	v_mfma_f32_16x16x32_bf16 v[2:5], v[154:157], v[66:69], v[2:5]
	global_load_dwordx4 v[50:53], v[50:51], off
	v_cvt_pk_bf16_f32 v67, v148, v149
	global_load_dwordx4 v[54:57], v[54:55], off
	v_cvt_pk_bf16_f32 v68, v150, v151
	global_load_dwordx4 v[42:45], v[42:43], off
	v_cvt_pk_bf16_f32 v66, v145, v147
	global_load_dwordx4 v[46:49], v[46:47], off
	v_cvt_pk_bf16_f32 v69, v152, v153
	global_load_dwordx4 v[14:17], v[14:15], off
	s_nop 0
	global_load_dwordx4 v[38:41], v[38:39], off
	s_waitcnt lgkmcnt(0)
	ds_read_b64_tr_b16 v[148:149], v119
	ds_read_b64_tr_b16 v[150:151], v119 offset:4608
	s_waitcnt lgkmcnt(0)
	v_mfma_f32_16x16x32_bf16 v[22:25], v[148:151], v[66:69], v[22:25]
	ds_read_b64_tr_b16 v[148:149], v119 offset:128
	ds_read_b64_tr_b16 v[150:151], v119 offset:4736
	s_waitcnt lgkmcnt(0)
	v_mfma_f32_16x16x32_bf16 v[34:37], v[148:151], v[66:69], v[34:37]
	ds_read_b64_tr_b16 v[148:149], v119 offset:256
	ds_read_b64_tr_b16 v[150:151], v119 offset:4864
	s_waitcnt lgkmcnt(0)
	v_mfma_f32_16x16x32_bf16 v[30:33], v[148:151], v[66:69], v[30:33]
	ds_read_b64_tr_b16 v[148:149], v119 offset:384
	ds_read_b64_tr_b16 v[150:151], v119 offset:4992
	s_waitcnt lgkmcnt(0)
	v_mfma_f32_16x16x32_bf16 v[26:29], v[148:151], v[66:69], v[26:29]
	ds_read_b64_tr_b16 v[148:149], v119 offset:512
	ds_read_b64_tr_b16 v[150:151], v119 offset:5120
	s_waitcnt lgkmcnt(0)
	v_mfma_f32_16x16x32_bf16 v[18:21], v[148:151], v[66:69], v[18:21]
	ds_read_b64_tr_b16 v[148:149], v119 offset:640
	ds_read_b64_tr_b16 v[150:151], v119 offset:5248
	s_waitcnt lgkmcnt(0)
	v_mfma_f32_16x16x32_bf16 v[10:13], v[148:151], v[66:69], v[10:13]
	ds_read_b64_tr_b16 v[148:149], v119 offset:768
	ds_read_b64_tr_b16 v[150:151], v119 offset:5376
	s_waitcnt lgkmcnt(0)
; #define LAS __attribute__((address_space(3)))
; __device__ __forceinline__ unsigned pk2(float lo, float hi) { const f32x2 v = {lo, hi}; return __builtin_bit_cast(unsigned, __builtin_convertvector(v, bf16x2_t)); }
; __device__ __forceinline__ s16x4 tr16(const LAS unsigned char* p) { return __builtin_bit_cast(s16x4, __builtin_amdgcn_ds_read_tr16_b64_v4i16((LAS s16x4*)p)); }
; __device__ __forceinline__ bf16x8 cat8(s16x4 lo, s16x4 hi) { return __builtin_shufflevector(lo, hi, 0, 1, 2, 3, 4, 5, 6, 7); }
; __device__ __forceinline__ f32x4 mfma16(bf16x8 a, bf16x8 b, f32x4 c) { return __builtin_amdgcn_mfma_f32_16x16x32_bf16(a, b, c, 0, 0, 0); }
; #define LDS_WAIT() asm volatile("s_waitcnt lgkmcnt(0)" ::: "memory")
; __device__ __forceinline__ int trw_off(int row, int c8  , int GP) { return (row >> 2) * GP + (((c8 >> 1) * 4 + (row & 3)) * 32) + (c8 & 1) * 16; }
; __device__ __forceinline__ void attn_phase(const bf16* proj, bf16* mixed, const float* rpb, const float* gain_a, LAS unsigned char* lds, int vb, int nb, int wave, int lane_in) {
;     ...
;         for (int w = 0; w < 8; ++w) {
; #pragma unroll
;             for (int i = 0; i < 8; ++i) { const int id = lane + 64 * i, j = id >> 4, ch = id & 15; *(LAS v4u*)(vt + trw_off(j, ch, 1152)) = vr[i]; }
;             if (w < 7) { const int vtok0 = base + 64 * (row_start + w + 1) + blk_start;
; #pragma unroll
;                 for (int i = 0; i < 8; ++i) { const int id = lane + 64 * i, j = id >> 4, ch = id & 15; vr[i] = *(const v4u*)(proj + (size_t)(vtok0 + j) * NIN + C_AV + h * 128 + ch * 8); } }
;             LDS_WAIT();
;             bf16x8 pb;
;             { v4u pw; pw.x = pk2(sc[2 * w][0], sc[2 * w][1]); pw.y = pk2(sc[2 * w][2], sc[2 * w][3]); pw.z = pk2(sc[2 * w + 1][0], sc[2 * w + 1][1]); pw.w = pk2(sc[2 * w + 1][2], sc[2 * w + 1][3]); pb = __builtin_bit_cast(bf16x8, pw); }
;             const LAS unsigned char* tb = vt + g * 1152 + (qi >> 2) * 32 + (qi & 3) * 8;
; #pragma unroll
;             for (int v = 0; v < 8; ++v) {
;                 const s16x4 lo = tr16(tb + v * 128), hi = tr16(tb + 4 * 1152 + v * 128);
;                 o[v] = mfma16(cat8(lo, hi), pb, o[v]);
;             }
;             LDS_WAIT();
	v_mfma_f32_16x16x32_bf16 v[6:9], v[148:151], v[66:69], v[6:9]
	ds_read_b64_tr_b16 v[148:149], v119 offset:896
	ds_read_b64_tr_b16 v[150:151], v119 offset:5504
	s_waitcnt lgkmcnt(0)
	s_waitcnt vmcnt(6)
	ds_write_b128 v72, v[62:65]
	ds_write_b128 v74, v[58:61]
	s_waitcnt vmcnt(4)
	ds_write_b128 v76, v[54:57]
	ds_write_b128 v78, v[50:53]
	s_waitcnt vmcnt(2)
	ds_write_b128 v80, v[46:49]
	ds_write_b128 v82, v[42:45]
	s_waitcnt vmcnt(0)
	ds_write_b128 v84, v[38:41]
	ds_write_b128 v86, v[14:17]
	v_add_u32_e32 v62, v97, v144
	v_add_u32_e32 v14, v62, v143
	v_mad_i64_i32 v[14:15], s[4:5], v14, s33, v[88:89]
	v_lshl_add_u64 v[14:15], v[14:15], 0, s[42:43]
	v_add_u32_e32 v38, v62, v142
	v_lshl_add_u64 v[14:15], v[14:15], 0, v[182:183]
	v_mad_i64_i32 v[38:39], s[4:5], v38, s33, v[88:89]
	v_add_co_u32_e32 v14, vcc, s25, v14
	v_lshl_add_u64 v[38:39], v[38:39], 0, s[42:43]
	v_add_u32_e32 v42, v62, v141
	v_addc_co_u32_e32 v15, vcc, 0, v15, vcc
	v_lshl_add_u64 v[38:39], v[38:39], 0, v[182:183]
	v_mad_i64_i32 v[42:43], s[4:5], v42, s33, v[88:89]
	v_add_co_u32_e32 v38, vcc, s25, v38
	v_lshl_add_u64 v[42:43], v[42:43], 0, s[42:43]
	v_add_u32_e32 v46, v62, v140
	v_addc_co_u32_e32 v39, vcc, 0, v39, vcc
	v_lshl_add_u64 v[42:43], v[42:43], 0, v[182:183]
	v_mad_i64_i32 v[46:47], s[4:5], v46, s33, v[88:89]
	v_add_co_u32_e32 v42, vcc, s25, v42
	v_lshl_add_u64 v[46:47], v[46:47], 0, s[42:43]
	v_add_u32_e32 v50, v62, v139
	v_addc_co_u32_e32 v43, vcc, 0, v43, vcc
	v_lshl_add_u64 v[46:47], v[46:47], 0, v[182:183]
	v_mad_i64_i32 v[50:51], s[4:5], v50, s33, v[88:89]
	v_add_co_u32_e32 v46, vcc, s25, v46
	v_lshl_add_u64 v[50:51], v[50:51], 0, s[42:43]
	v_add_u32_e32 v54, v62, v138
	v_addc_co_u32_e32 v47, vcc, 0, v47, vcc
	v_lshl_add_u64 v[50:51], v[50:51], 0, v[182:183]
	v_mad_i64_i32 v[54:55], s[4:5], v54, s33, v[88:89]
	v_add_co_u32_e32 v50, vcc, s25, v50
	v_lshl_add_u64 v[54:55], v[54:55], 0, s[42:43]
	v_add_u32_e32 v58, v62, v137
	v_addc_co_u32_e32 v51, vcc, 0, v51, vcc
	v_lshl_add_u64 v[54:55], v[54:55], 0, v[182:183]
	v_mad_i64_i32 v[58:59], s[4:5], v58, s33, v[88:89]
	v_add_co_u32_e32 v54, vcc, s25, v54
	v_lshl_add_u64 v[58:59], v[58:59], 0, s[42:43]
	v_add_u32_e32 v62, v62, v71
	v_addc_co_u32_e32 v55, vcc, 0, v55, vcc
	v_lshl_add_u64 v[58:59], v[58:59], 0, v[182:183]
	v_mad_i64_i32 v[62:63], s[4:5], v62, s33, v[88:89]
	v_add_co_u32_e32 v58, vcc, s25, v58
	v_lshl_add_u64 v[62:63], v[62:63], 0, s[42:43]
	s_nop 0
	v_addc_co_u32_e32 v59, vcc, 0, v59, vcc
	v_lshl_add_u64 v[62:63], v[62:63], 0, v[182:183]
	v_add_co_u32_e32 v62, vcc, s25, v62
	global_load_dwordx4 v[58:61], v[58:59], off
	s_nop 0
	v_addc_co_u32_e32 v63, vcc, 0, v63, vcc
	global_load_dwordx4 v[62:65], v[62:63], off
	s_waitcnt lgkmcnt(8)
	v_mfma_f32_16x16x32_bf16 v[2:5], v[148:151], v[66:69], v[2:5]
	global_load_dwordx4 v[50:53], v[50:51], off
	s_nop 0
	global_load_dwordx4 v[54:57], v[54:55], off
	s_nop 0
	global_load_dwordx4 v[42:45], v[42:43], off
	s_nop 0
	global_load_dwordx4 v[46:49], v[46:47], off
	s_nop 0
	global_load_dwordx4 v[14:17], v[14:15], off
	s_nop 0
	global_load_dwordx4 v[38:41], v[38:39], off
	s_waitcnt lgkmcnt(0)
	ds_read_b64_tr_b16 v[66:67], v119
	ds_read_b64_tr_b16 v[68:69], v119 offset:4608
	s_waitcnt lgkmcnt(0)
	v_mfma_f32_16x16x32_bf16 v[22:25], v[66:69], v[128:131], v[22:25]
	ds_read_b64_tr_b16 v[66:67], v119 offset:128
	ds_read_b64_tr_b16 v[68:69], v119 offset:4736
	s_waitcnt lgkmcnt(0)
	v_mfma_f32_16x16x32_bf16 v[34:37], v[66:69], v[128:131], v[34:37]
	ds_read_b64_tr_b16 v[66:67], v119 offset:256
	ds_read_b64_tr_b16 v[68:69], v119 offset:4864
	s_waitcnt lgkmcnt(0)
	v_mfma_f32_16x16x32_bf16 v[30:33], v[66:69], v[128:131], v[30:33]
	ds_read_b64_tr_b16 v[66:67], v119 offset:384
	ds_read_b64_tr_b16 v[68:69], v119 offset:4992
	s_waitcnt lgkmcnt(0)
	v_mfma_f32_16x16x32_bf16 v[26:29], v[66:69], v[128:131], v[26:29]
	ds_read_b64_tr_b16 v[66:67], v119 offset:512
	ds_read_b64_tr_b16 v[68:69], v119 offset:5120
	s_waitcnt lgkmcnt(0)
	v_mfma_f32_16x16x32_bf16 v[66:69], v[66:69], v[128:131], v[18:21]
	s_nop 2
	ds_read_b64_tr_b16 v[18:19], v119 offset:640
	ds_read_b64_tr_b16 v[20:21], v119 offset:5248
	s_waitcnt lgkmcnt(0)
	v_mfma_f32_16x16x32_bf16 v[10:13], v[18:21], v[128:131], v[10:13]
	ds_read_b64_tr_b16 v[18:19], v119 offset:768
	ds_read_b64_tr_b16 v[20:21], v119 offset:5376
	s_waitcnt lgkmcnt(0)
	v_mfma_f32_16x16x32_bf16 v[6:9], v[18:21], v[128:131], v[6:9]
	ds_read_b64_tr_b16 v[18:19], v119 offset:896
	ds_read_b64_tr_b16 v[20:21], v119 offset:5504
	s_waitcnt lgkmcnt(0)
	s_waitcnt vmcnt(6)
	ds_write_b128 v72, v[62:65]
	ds_write_b128 v74, v[58:61]
	s_waitcnt vmcnt(4)
	ds_write_b128 v76, v[54:57]
	ds_write_b128 v78, v[50:53]
	s_waitcnt vmcnt(2)
	ds_write_b128 v80, v[46:49]
	ds_write_b128 v82, v[42:45]
	s_waitcnt vmcnt(0)
	ds_write_b128 v84, v[38:41]
	ds_write_b128 v86, v[14:17]
	s_waitcnt lgkmcnt(8)
; #define LAS __attribute__((address_space(3)))
; __device__ __forceinline__ unsigned pk2(float lo, float hi) { const f32x2 v = {lo, hi}; return __builtin_bit_cast(unsigned, __builtin_convertvector(v, bf16x2_t)); }
; __device__ __forceinline__ s16x4 tr16(const LAS unsigned char* p) { return __builtin_bit_cast(s16x4, __builtin_amdgcn_ds_read_tr16_b64_v4i16((LAS s16x4*)p)); }
; __device__ __forceinline__ bf16x8 cat8(s16x4 lo, s16x4 hi) { return __builtin_shufflevector(lo, hi, 0, 1, 2, 3, 4, 5, 6, 7); }
; __device__ __forceinline__ f32x4 mfma16(bf16x8 a, bf16x8 b, f32x4 c) { return __builtin_amdgcn_mfma_f32_16x16x32_bf16(a, b, c, 0, 0, 0); }
; #define LDS_WAIT() asm volatile("s_waitcnt lgkmcnt(0)" ::: "memory")
; __device__ __forceinline__ int trw_off(int row, int c8  , int GP) { return (row >> 2) * GP + (((c8 >> 1) * 4 + (row & 3)) * 32) + (c8 & 1) * 16; }
; __device__ __forceinline__ void attn_phase(const bf16* proj, bf16* mixed, const float* rpb, const float* gain_a, LAS unsigned char* lds, int vb, int nb, int wave, int lane_in) {
;     ...
;         for (int w = 0; w < 8; ++w) {
; #pragma unroll
;             for (int i = 0; i < 8; ++i) { const int id = lane + 64 * i, j = id >> 4, ch = id & 15; *(LAS v4u*)(vt + trw_off(j, ch, 1152)) = vr[i]; }
;             if (w < 7) { const int vtok0 = base + 64 * (row_start + w + 1) + blk_start;
; #pragma unroll
;                 for (int i = 0; i < 8; ++i) { const int id = lane + 64 * i, j = id >> 4, ch = id & 15; vr[i] = *(const v4u*)(proj + (size_t)(vtok0 + j) * NIN + C_AV + h * 128 + ch * 8); } }
;             LDS_WAIT();
;             bf16x8 pb;
;             { v4u pw; pw.x = pk2(sc[2 * w][0], sc[2 * w][1]); pw.y = pk2(sc[2 * w][2], sc[2 * w][3]); pw.z = pk2(sc[2 * w + 1][0], sc[2 * w + 1][1]); pw.w = pk2(sc[2 * w + 1][2], sc[2 * w + 1][3]); pb = __builtin_bit_cast(bf16x8, pw); }
;             const LAS unsigned char* tb = vt + g * 1152 + (qi >> 2) * 32 + (qi & 3) * 8;
; #pragma unroll
;             for (int v = 0; v < 8; ++v) {
;                 const s16x4 lo = tr16(tb + v * 128), hi = tr16(tb + 4 * 1152 + v * 128);
;                 o[v] = mfma16(cat8(lo, hi), pb, o[v]);
;             }
;             LDS_WAIT();
	v_mfma_f32_16x16x32_bf16 v[2:5], v[18:21], v[128:131], v[2:5]
	v_add_u32_e32 v20, v94, v144
	v_add_u32_e32 v14, v20, v143
	v_mad_i64_i32 v[14:15], s[4:5], v14, s33, v[88:89]
	v_lshl_add_u64 v[14:15], v[14:15], 0, s[42:43]
	v_add_u32_e32 v18, v20, v142
	v_lshl_add_u64 v[14:15], v[14:15], 0, v[182:183]
	v_mad_i64_i32 v[18:19], s[4:5], v18, s33, v[88:89]
	v_add_co_u32_e32 v14, vcc, s25, v14
	v_lshl_add_u64 v[18:19], v[18:19], 0, s[42:43]
	s_nop 0
	v_addc_co_u32_e32 v15, vcc, 0, v15, vcc
	v_lshl_add_u64 v[18:19], v[18:19], 0, v[182:183]
	v_add_co_u32_e32 v18, vcc, s25, v18
	global_load_dwordx4 v[14:17], v[14:15], off
	s_nop 0
	v_addc_co_u32_e32 v19, vcc, 0, v19, vcc
	global_load_dwordx4 v[38:41], v[18:19], off
	v_add_u32_e32 v18, v20, v141
	v_mad_i64_i32 v[18:19], s[4:5], v18, s33, v[88:89]
	v_lshl_add_u64 v[18:19], v[18:19], 0, s[42:43]
	v_lshl_add_u64 v[18:19], v[18:19], 0, v[182:183]
	v_add_co_u32_e32 v18, vcc, s25, v18
	s_nop 1
	v_addc_co_u32_e32 v19, vcc, 0, v19, vcc
	global_load_dwordx4 v[42:45], v[18:19], off
	v_add_u32_e32 v18, v20, v140
	v_mad_i64_i32 v[18:19], s[4:5], v18, s33, v[88:89]
	v_lshl_add_u64 v[18:19], v[18:19], 0, s[42:43]
	v_lshl_add_u64 v[18:19], v[18:19], 0, v[182:183]
	v_add_co_u32_e32 v18, vcc, s25, v18
	s_nop 1
	v_addc_co_u32_e32 v19, vcc, 0, v19, vcc
	global_load_dwordx4 v[46:49], v[18:19], off
	v_add_u32_e32 v18, v20, v139
	v_mad_i64_i32 v[18:19], s[4:5], v18, s33, v[88:89]
	v_lshl_add_u64 v[18:19], v[18:19], 0, s[42:43]
	v_lshl_add_u64 v[18:19], v[18:19], 0, v[182:183]
	v_add_co_u32_e32 v18, vcc, s25, v18
	s_nop 1
	v_addc_co_u32_e32 v19, vcc, 0, v19, vcc
	global_load_dwordx4 v[50:53], v[18:19], off
	v_add_u32_e32 v18, v20, v138
	v_mad_i64_i32 v[18:19], s[4:5], v18, s33, v[88:89]
	v_lshl_add_u64 v[18:19], v[18:19], 0, s[42:43]
	v_lshl_add_u64 v[18:19], v[18:19], 0, v[182:183]
	v_add_co_u32_e32 v18, vcc, s25, v18
	s_nop 1
	v_addc_co_u32_e32 v19, vcc, 0, v19, vcc
	global_load_dwordx4 v[54:57], v[18:19], off
	v_add_u32_e32 v18, v20, v137
	v_mad_i64_i32 v[18:19], s[4:5], v18, s33, v[88:89]
	v_lshl_add_u64 v[18:19], v[18:19], 0, s[42:43]
	v_lshl_add_u64 v[18:19], v[18:19], 0, v[182:183]
	v_add_co_u32_e32 v18, vcc, s25, v18
	s_nop 1
	v_addc_co_u32_e32 v19, vcc, 0, v19, vcc
	global_load_dwordx4 v[58:61], v[18:19], off
	v_add_u32_e32 v18, v20, v71
	v_mad_i64_i32 v[18:19], s[4:5], v18, s33, v[88:89]
	v_lshl_add_u64 v[18:19], v[18:19], 0, s[42:43]
	v_lshl_add_u64 v[18:19], v[18:19], 0, v[182:183]
	v_add_co_u32_e32 v18, vcc, s25, v18
	s_nop 1
	v_addc_co_u32_e32 v19, vcc, 0, v19, vcc
	global_load_dwordx4 v[62:65], v[18:19], off
	s_waitcnt lgkmcnt(0)
	ds_read_b64_tr_b16 v[18:19], v119
	ds_read_b64_tr_b16 v[20:21], v119 offset:4608
	s_waitcnt lgkmcnt(0)
	v_mfma_f32_16x16x32_bf16 v[18:21], v[18:21], v[120:123], v[22:25]
	s_nop 2
	ds_read_b64_tr_b16 v[22:23], v119 offset:128
	ds_read_b64_tr_b16 v[24:25], v119 offset:4736
	s_waitcnt lgkmcnt(0)
	v_mfma_f32_16x16x32_bf16 v[22:25], v[22:25], v[120:123], v[34:37]
	s_nop 2
	ds_read_b64_tr_b16 v[34:35], v119 offset:256
	ds_read_b64_tr_b16 v[36:37], v119 offset:4864
	s_waitcnt lgkmcnt(0)
	v_mfma_f32_16x16x32_bf16 v[34:37], v[34:37], v[120:123], v[30:33]
	s_nop 2
	ds_read_b64_tr_b16 v[30:31], v119 offset:384
	ds_read_b64_tr_b16 v[32:33], v119 offset:4992
	s_waitcnt lgkmcnt(0)
	v_mfma_f32_16x16x32_bf16 v[30:33], v[30:33], v[120:123], v[26:29]
	s_nop 2
	ds_read_b64_tr_b16 v[26:27], v119 offset:512
	ds_read_b64_tr_b16 v[28:29], v119 offset:5120
	s_waitcnt lgkmcnt(0)
	v_mfma_f32_16x16x32_bf16 v[26:29], v[26:29], v[120:123], v[66:69]
	s_nop 2
	ds_read_b64_tr_b16 v[66:67], v119 offset:640
	ds_read_b64_tr_b16 v[68:69], v119 offset:5248
	s_waitcnt lgkmcnt(0)
	v_mfma_f32_16x16x32_bf16 v[10:13], v[66:69], v[120:123], v[10:13]
	ds_read_b64_tr_b16 v[66:67], v119 offset:768
	ds_read_b64_tr_b16 v[68:69], v119 offset:5376
	s_waitcnt lgkmcnt(0)
	v_mfma_f32_16x16x32_bf16 v[6:9], v[66:69], v[120:123], v[6:9]
	ds_read_b64_tr_b16 v[66:67], v119 offset:896
	ds_read_b64_tr_b16 v[68:69], v119 offset:5504
	s_waitcnt lgkmcnt(0)
	s_waitcnt vmcnt(0)
	ds_write_b128 v72, v[62:65]
	ds_write_b128 v74, v[58:61]
	ds_write_b128 v76, v[54:57]
	ds_write_b128 v78, v[50:53]
	ds_write_b128 v80, v[46:49]
	ds_write_b128 v82, v[42:45]
	ds_write_b128 v84, v[38:41]
	ds_write_b128 v86, v[14:17]
	v_add_u32_e32 v62, v93, v144
	v_add_u32_e32 v14, v62, v143
	v_mad_i64_i32 v[14:15], s[4:5], v14, s33, v[88:89]
	v_lshl_add_u64 v[14:15], v[14:15], 0, s[42:43]
	v_add_u32_e32 v38, v62, v142
	v_lshl_add_u64 v[14:15], v[14:15], 0, v[182:183]
	v_mad_i64_i32 v[38:39], s[4:5], v38, s33, v[88:89]
	v_add_co_u32_e32 v14, vcc, s25, v14
	v_lshl_add_u64 v[38:39], v[38:39], 0, s[42:43]
	v_add_u32_e32 v42, v62, v141
	v_addc_co_u32_e32 v15, vcc, 0, v15, vcc
	v_lshl_add_u64 v[38:39], v[38:39], 0, v[182:183]
	v_mad_i64_i32 v[42:43], s[4:5], v42, s33, v[88:89]
	v_add_co_u32_e32 v38, vcc, s25, v38
	v_lshl_add_u64 v[42:43], v[42:43], 0, s[42:43]
	v_add_u32_e32 v46, v62, v140
	v_addc_co_u32_e32 v39, vcc, 0, v39, vcc
	v_lshl_add_u64 v[42:43], v[42:43], 0, v[182:183]
	v_mad_i64_i32 v[46:47], s[4:5], v46, s33, v[88:89]
	v_add_co_u32_e32 v42, vcc, s25, v42
	v_lshl_add_u64 v[46:47], v[46:47], 0, s[42:43]
	v_add_u32_e32 v50, v62, v139
	v_addc_co_u32_e32 v43, vcc, 0, v43, vcc
	v_lshl_add_u64 v[46:47], v[46:47], 0, v[182:183]
	v_mad_i64_i32 v[50:51], s[4:5], v50, s33, v[88:89]
	v_add_co_u32_e32 v46, vcc, s25, v46
	v_lshl_add_u64 v[50:51], v[50:51], 0, s[42:43]
	v_add_u32_e32 v54, v62, v138
	v_addc_co_u32_e32 v47, vcc, 0, v47, vcc
	v_lshl_add_u64 v[50:51], v[50:51], 0, v[182:183]
	v_mad_i64_i32 v[54:55], s[4:5], v54, s33, v[88:89]
	v_add_co_u32_e32 v50, vcc, s25, v50
	v_lshl_add_u64 v[54:55], v[54:55], 0, s[42:43]
	v_add_u32_e32 v58, v62, v137
	v_addc_co_u32_e32 v51, vcc, 0, v51, vcc
	v_lshl_add_u64 v[54:55], v[54:55], 0, v[182:183]
	v_mad_i64_i32 v[58:59], s[4:5], v58, s33, v[88:89]
	v_add_co_u32_e32 v54, vcc, s25, v54
	v_lshl_add_u64 v[58:59], v[58:59], 0, s[42:43]
	v_add_u32_e32 v62, v62, v71
	v_addc_co_u32_e32 v55, vcc, 0, v55, vcc
	v_lshl_add_u64 v[58:59], v[58:59], 0, v[182:183]
	v_mad_i64_i32 v[62:63], s[4:5], v62, s33, v[88:89]
	v_add_co_u32_e32 v58, vcc, s25, v58
	v_lshl_add_u64 v[62:63], v[62:63], 0, s[42:43]
	s_nop 0
	v_addc_co_u32_e32 v59, vcc, 0, v59, vcc
	v_lshl_add_u64 v[62:63], v[62:63], 0, v[182:183]
	v_add_co_u32_e32 v62, vcc, s25, v62
	global_load_dwordx4 v[58:61], v[58:59], off
	s_nop 0
	v_addc_co_u32_e32 v63, vcc, 0, v63, vcc
	global_load_dwordx4 v[62:65], v[62:63], off
	s_waitcnt lgkmcnt(8)
; #define LAS __attribute__((address_space(3)))
; __device__ __forceinline__ unsigned pk2(float lo, float hi) { const f32x2 v = {lo, hi}; return __builtin_bit_cast(unsigned, __builtin_convertvector(v, bf16x2_t)); }
; __device__ __forceinline__ s16x4 tr16(const LAS unsigned char* p) { return __builtin_bit_cast(s16x4, __builtin_amdgcn_ds_read_tr16_b64_v4i16((LAS s16x4*)p)); }
; __device__ __forceinline__ bf16x8 cat8(s16x4 lo, s16x4 hi) { return __builtin_shufflevector(lo, hi, 0, 1, 2, 3, 4, 5, 6, 7); }
; __device__ __forceinline__ f32x4 mfma16(bf16x8 a, bf16x8 b, f32x4 c) { return __builtin_amdgcn_mfma_f32_16x16x32_bf16(a, b, c, 0, 0, 0); }
; #define LDS_WAIT() asm volatile("s_waitcnt lgkmcnt(0)" ::: "memory")
; __device__ __forceinline__ void attn_phase(const bf16* proj, bf16* mixed, const float* rpb, const float* gain_a, LAS unsigned char* lds, int vb, int nb, int wave, int lane_in) {
;     ...
;         for (int w = 0; w < 8; ++w) {
; #pragma unroll
;             for (int i = 0; i < 8; ++i) { const int id = lane + 64 * i, j = id >> 4, ch = id & 15; *(LAS v4u*)(vt + trw_off(j, ch, 1152)) = vr[i]; }
;             if (w < 7) { const int vtok0 = base + 64 * (row_start + w + 1) + blk_start;
; #pragma unroll
;                 for (int i = 0; i < 8; ++i) { const int id = lane + 64 * i, j = id >> 4, ch = id & 15; vr[i] = *(const v4u*)(proj + (size_t)(vtok0 + j) * NIN + C_AV + h * 128 + ch * 8); } }
;             LDS_WAIT();
;             bf16x8 pb;
;             { v4u pw; pw.x = pk2(sc[2 * w][0], sc[2 * w][1]); pw.y = pk2(sc[2 * w][2], sc[2 * w][3]); pw.z = pk2(sc[2 * w + 1][0], sc[2 * w + 1][1]); pw.w = pk2(sc[2 * w + 1][2], sc[2 * w + 1][3]); pb = __builtin_bit_cast(bf16x8, pw); }
;             const LAS unsigned char* tb = vt + g * 1152 + (qi >> 2) * 32 + (qi & 3) * 8;
; #pragma unroll
;             for (int v = 0; v < 8; ++v) {
;                 const s16x4 lo = tr16(tb + v * 128), hi = tr16(tb + 4 * 1152 + v * 128);
;                 o[v] = mfma16(cat8(lo, hi), pb, o[v]);
;             }
;             LDS_WAIT();
;         }
;         const float inv = 1.0f / sum;
;         float ssq = 0.f;
; #pragma unroll
;         for (int v = 0; v < 8; ++v) { o[v] = o[v] * inv; ssq += (o[v].x * o[v].x + o[v].y * o[v].y) + (o[v].z * o[v].z + o[v].w * o[v].w); }
;         ssq += __shfl_xor(ssq, 16); ssq += __shfl_xor(ssq, 32);
;         if (g == 0) ssx[wave * 16 + qi] = ssq;
	v_mfma_f32_16x16x32_bf16 v[2:5], v[66:69], v[120:123], v[2:5]
	global_load_dwordx4 v[50:53], v[50:51], off
	v_cvt_pk_bf16_f32 v66, v110, v111
	global_load_dwordx4 v[54:57], v[54:55], off
	v_cvt_pk_bf16_f32 v67, v112, v113
	global_load_dwordx4 v[42:45], v[42:43], off
	v_cvt_pk_bf16_f32 v68, v114, v115
	global_load_dwordx4 v[46:49], v[46:47], off
	v_cvt_pk_bf16_f32 v69, v116, v117
	global_load_dwordx4 v[14:17], v[14:15], off
	s_nop 0
	global_load_dwordx4 v[38:41], v[38:39], off
	s_waitcnt lgkmcnt(0)
	ds_read_b64_tr_b16 v[110:111], v119
	ds_read_b64_tr_b16 v[112:113], v119 offset:4608
	s_waitcnt lgkmcnt(0)
	v_mfma_f32_16x16x32_bf16 v[18:21], v[110:113], v[66:69], v[18:21]
	ds_read_b64_tr_b16 v[110:111], v119 offset:128
	ds_read_b64_tr_b16 v[112:113], v119 offset:4736
	s_waitcnt lgkmcnt(0)
	v_mfma_f32_16x16x32_bf16 v[22:25], v[110:113], v[66:69], v[22:25]
	ds_read_b64_tr_b16 v[110:111], v119 offset:256
	ds_read_b64_tr_b16 v[112:113], v119 offset:4864
	s_waitcnt lgkmcnt(0)
	v_mfma_f32_16x16x32_bf16 v[34:37], v[110:113], v[66:69], v[34:37]
	ds_read_b64_tr_b16 v[110:111], v119 offset:384
	ds_read_b64_tr_b16 v[112:113], v119 offset:4992
	s_waitcnt lgkmcnt(0)
	v_mfma_f32_16x16x32_bf16 v[30:33], v[110:113], v[66:69], v[30:33]
	ds_read_b64_tr_b16 v[110:111], v119 offset:512
	ds_read_b64_tr_b16 v[112:113], v119 offset:5120
	s_waitcnt lgkmcnt(0)
	v_mfma_f32_16x16x32_bf16 v[26:29], v[110:113], v[66:69], v[26:29]
	ds_read_b64_tr_b16 v[110:111], v119 offset:640
	ds_read_b64_tr_b16 v[112:113], v119 offset:5248
	s_waitcnt lgkmcnt(0)
	v_mfma_f32_16x16x32_bf16 v[10:13], v[110:113], v[66:69], v[10:13]
	ds_read_b64_tr_b16 v[110:111], v119 offset:768
	ds_read_b64_tr_b16 v[112:113], v119 offset:5376
	s_waitcnt lgkmcnt(0)
	v_mfma_f32_16x16x32_bf16 v[6:9], v[110:113], v[66:69], v[6:9]
	ds_read_b64_tr_b16 v[110:111], v119 offset:896
	ds_read_b64_tr_b16 v[112:113], v119 offset:5504
	s_waitcnt lgkmcnt(0)
	s_waitcnt vmcnt(6)
	ds_write_b128 v72, v[62:65]
	ds_write_b128 v74, v[58:61]
	s_waitcnt vmcnt(4)
	ds_write_b128 v76, v[54:57]
	ds_write_b128 v78, v[50:53]
	s_waitcnt vmcnt(2)
	ds_write_b128 v80, v[46:49]
	ds_write_b128 v82, v[42:45]
	s_waitcnt vmcnt(0)
	ds_write_b128 v84, v[38:41]
	ds_write_b128 v86, v[14:17]
	s_waitcnt lgkmcnt(0)
	ds_read_b64_tr_b16 v[38:39], v119
	ds_read_b64_tr_b16 v[40:41], v119 offset:4608
	v_cvt_pk_bf16_f32 v14, v101, v102
	v_cvt_pk_bf16_f32 v15, v103, v104
	v_cvt_pk_bf16_f32 v16, v105, v106
	v_cvt_pk_bf16_f32 v17, v107, v108
	s_waitcnt lgkmcnt(10)
	v_mfma_f32_16x16x32_bf16 v[2:5], v[110:113], v[66:69], v[2:5]
	s_waitcnt lgkmcnt(0)
	v_mfma_f32_16x16x32_bf16 v[18:21], v[38:41], v[14:17], v[18:21]
	ds_read_b64_tr_b16 v[38:39], v119 offset:128
	ds_read_b64_tr_b16 v[40:41], v119 offset:4736
	s_waitcnt lgkmcnt(0)
	v_mfma_f32_16x16x32_bf16 v[22:25], v[38:41], v[14:17], v[22:25]
	ds_read_b64_tr_b16 v[38:39], v119 offset:256
	ds_read_b64_tr_b16 v[40:41], v119 offset:4864
	s_waitcnt lgkmcnt(0)
	v_mfma_f32_16x16x32_bf16 v[38:41], v[38:41], v[14:17], v[34:37]
	s_nop 2
	ds_read_b64_tr_b16 v[34:35], v119 offset:384
	ds_read_b64_tr_b16 v[36:37], v119 offset:4992
	s_waitcnt lgkmcnt(0)
	v_mfma_f32_16x16x32_bf16 v[30:33], v[34:37], v[14:17], v[30:33]
	ds_read_b64_tr_b16 v[34:35], v119 offset:512
	ds_read_b64_tr_b16 v[36:37], v119 offset:5120
	s_waitcnt lgkmcnt(0)
	v_mfma_f32_16x16x32_bf16 v[42:45], v[34:37], v[14:17], v[26:29]
	s_nop 2
	ds_read_b64_tr_b16 v[26:27], v119 offset:640
	ds_read_b64_tr_b16 v[28:29], v119 offset:5248
	s_waitcnt lgkmcnt(0)
	v_mfma_f32_16x16x32_bf16 v[46:49], v[26:29], v[14:17], v[10:13]
	s_nop 2
	ds_read_b64_tr_b16 v[10:11], v119 offset:768
	ds_read_b64_tr_b16 v[12:13], v119 offset:5376
	s_waitcnt lgkmcnt(0)
	v_mfma_f32_16x16x32_bf16 v[50:53], v[10:13], v[14:17], v[6:9]
	s_nop 2
	ds_read_b64_tr_b16 v[6:7], v119 offset:896
	ds_read_b64_tr_b16 v[8:9], v119 offset:5504
	s_waitcnt lgkmcnt(0)
	s_waitcnt lgkmcnt(0)
	v_mfma_f32_16x16x32_bf16 v[54:57], v[6:9], v[14:17], v[2:5]
	s_nop 2
	v_add_f32_e32 v2, v99, v100
	v_div_scale_f32 v3, s[4:5], v2, v2, 1.0
	v_rcp_f32_e32 v4, v3
	s_nop 0
	v_fma_f32 v5, -v3, v4, 1.0
	v_fmac_f32_e32 v4, v5, v4
	v_div_scale_f32 v5, vcc, 1.0, v2, 1.0
	v_mul_f32_e32 v6, v5, v4
	v_fma_f32 v7, -v3, v6, v5
	v_fmac_f32_e32 v6, v7, v4
	v_fma_f32 v3, -v3, v6, v5
	v_div_fmas_f32 v3, v3, v4, v6
	v_div_fixup_f32 v4, v3, v2, 1.0
	v_pk_mul_f32 v[34:35], v[4:5], v[20:21] op_sel_hi:[0,1]
	v_pk_mul_f32 v[36:37], v[4:5], v[18:19] op_sel_hi:[0,1]
	v_mul_f32_e32 v2, v37, v37
	v_mul_f32_e32 v3, v35, v35
	v_fmac_f32_e32 v2, v36, v36
	v_fmac_f32_e32 v3, v34, v34
	v_pk_mul_f32 v[26:27], v[4:5], v[24:25] op_sel_hi:[0,1]
	v_pk_mul_f32 v[28:29], v[4:5], v[22:23] op_sel_hi:[0,1]
	v_add_f32_e32 v2, v2, v3
	v_mul_f32_e32 v3, v29, v29
	v_mul_f32_e32 v5, v27, v27
	v_fmac_f32_e32 v3, v28, v28
	v_fmac_f32_e32 v5, v26, v26
	v_add_f32_e32 v3, v3, v5
	v_pk_mul_f32 v[22:23], v[4:5], v[40:41] op_sel_hi:[0,1]
	v_pk_mul_f32 v[24:25], v[4:5], v[38:39] op_sel_hi:[0,1]
	v_add_f32_e32 v2, v2, v3
	v_mul_f32_e32 v3, v25, v25
	v_mul_f32_e32 v5, v23, v23
	v_fmac_f32_e32 v3, v24, v24
	v_fmac_f32_e32 v5, v22, v22
	v_add_f32_e32 v3, v3, v5
	v_pk_mul_f32 v[18:19], v[4:5], v[32:33] op_sel_hi:[0,1]
	v_pk_mul_f32 v[20:21], v[4:5], v[30:31] op_sel_hi:[0,1]
	v_add_f32_e32 v2, v2, v3
	v_mul_f32_e32 v3, v21, v21
	v_mul_f32_e32 v5, v19, v19
	v_fmac_f32_e32 v3, v20, v20
	v_fmac_f32_e32 v5, v18, v18
	v_add_f32_e32 v3, v3, v5
	v_pk_mul_f32 v[14:15], v[4:5], v[44:45] op_sel_hi:[0,1]
	v_pk_mul_f32 v[16:17], v[4:5], v[42:43] op_sel_hi:[0,1]
	v_add_f32_e32 v2, v2, v3
	v_mul_f32_e32 v3, v17, v17
	v_mul_f32_e32 v5, v15, v15
	v_fmac_f32_e32 v3, v16, v16
	v_fmac_f32_e32 v5, v14, v14
	v_add_f32_e32 v3, v3, v5
	v_pk_mul_f32 v[10:11], v[4:5], v[48:49] op_sel_hi:[0,1]
	v_pk_mul_f32 v[12:13], v[4:5], v[46:47] op_sel_hi:[0,1]
	v_add_f32_e32 v2, v2, v3
	v_mul_f32_e32 v3, v13, v13
	v_mul_f32_e32 v5, v11, v11
	v_fmac_f32_e32 v3, v12, v12
	v_fmac_f32_e32 v5, v10, v10
	v_add_f32_e32 v3, v3, v5
	v_pk_mul_f32 v[6:7], v[4:5], v[52:53] op_sel_hi:[0,1]
	v_pk_mul_f32 v[8:9], v[4:5], v[50:51] op_sel_hi:[0,1]
	v_add_f32_e32 v2, v2, v3
	v_mul_f32_e32 v3, v9, v9
	v_mul_f32_e32 v5, v7, v7
	v_fmac_f32_e32 v3, v8, v8
	v_fmac_f32_e32 v5, v6, v6
	v_add_f32_e32 v3, v3, v5
	v_add_f32_e32 v30, v2, v3
	v_pk_mul_f32 v[2:3], v[4:5], v[56:57] op_sel_hi:[0,1]
	v_pk_mul_f32 v[4:5], v[4:5], v[54:55] op_sel_hi:[0,1]
	v_mul_f32_e32 v31, v5, v5
	v_mul_f32_e32 v32, v3, v3
	v_fmac_f32_e32 v31, v4, v4
	v_fmac_f32_e32 v32, v2, v2
	v_add_f32_e32 v31, v31, v32
	v_add_f32_e32 v30, v30, v31
	ds_bpermute_b32 v31, v95, v30
	v_cmp_gt_u32_e32 vcc, 16, v1
	s_waitcnt lgkmcnt(0)
	v_add_f32_e32 v30, v30, v31
	ds_bpermute_b32 v31, v96, v30
	s_and_saveexec_b64 s[4:5], vcc
	s_cbranch_execz .LBB0_425
	s_waitcnt lgkmcnt(0)
	v_add_f32_e32 v30, v30, v31
	v_lshl_add_u32 v1, v1, 2, s17
	ds_write_b32 v1, v30
	s_branch .LBB0_425

; __device__ __forceinline__ void hyena_norm(const float* ZT, const float* gain, bf16* mixed, LAS unsigned char* lds, int vb, int nb, int wave, int lane) {
;     ...
;         const float* src = ZT + (size_t)(wave * 128) * MTOK + R0 + lane;
;         float ss = 0.f;
;         for (int c = 0; c < 128; ++c) { const float v = src[(size_t)c * MTOK]; ss += v * v; }
;         ssx[wave * 64 + lane] = ss;
;         __syncthreads();
;         float tot = 0.f;
; #pragma unroll
;         for (int w = 0; w < 8; ++w) tot += ssx[w * 64 + lane];
;         const float rstd = 1.0f / sqrtf(tot * (1.0f / 1024.0f) + 1e-6f);
;         for (int cb = 0; cb < 2; ++cb) {
;             const int c0 = wave * 128 + cb * 64;
;             for (int cc = 0; cc < 64; ++cc) tile[cc * 65 + lane] = src[(size_t)(cb * 64 + cc) * MTOK] * rstd;
.LBB0_825:
	v_lshl_add_u64 v[14:15], v[12:13], 0, s[4:5]
	v_add_co_u32_e32 v20, vcc, 0x90200000, v14
	s_add_u32 s4, s4, 0x180000
	s_nop 0
	v_addc_co_u32_e32 v21, vcc, 0, v15, vcc
	global_load_dword v100, v[20:21], off
	s_addc_u32 s5, s5, 0
	s_cmp_eq_u32 s4, 0xc00000
	v_add_co_u32_e32 v20, vcc, 0x90218000, v14
	s_nop 1
	v_addc_co_u32_e32 v21, vcc, 0, v15, vcc
	global_load_dword v101, v[20:21], off
	v_add_co_u32_e32 v20, vcc, 0x90230000, v14
	s_nop 1
	v_addc_co_u32_e32 v21, vcc, 0, v15, vcc
	global_load_dword v102, v[20:21], off
	v_add_co_u32_e32 v20, vcc, 0x90248000, v14
	s_nop 1
	v_addc_co_u32_e32 v21, vcc, 0, v15, vcc
	global_load_dword v103, v[20:21], off
	v_add_co_u32_e32 v20, vcc, 0x90260000, v14
	s_nop 1
	v_addc_co_u32_e32 v21, vcc, 0, v15, vcc
	global_load_dword v104, v[20:21], off
	v_add_co_u32_e32 v20, vcc, 0x90278000, v14
	s_nop 1
	v_addc_co_u32_e32 v21, vcc, 0, v15, vcc
	global_load_dword v105, v[20:21], off
	v_add_co_u32_e32 v20, vcc, 0x90290000, v14
	s_nop 1
	v_addc_co_u32_e32 v21, vcc, 0, v15, vcc
	global_load_dword v106, v[20:21], off
	v_add_co_u32_e32 v20, vcc, 0x902a8000, v14
	s_nop 1
	v_addc_co_u32_e32 v21, vcc, 0, v15, vcc
	global_load_dword v107, v[20:21], off
	v_add_co_u32_e32 v20, vcc, 0x902c0000, v14
	s_nop 1
	v_addc_co_u32_e32 v21, vcc, 0, v15, vcc
	global_load_dword v108, v[20:21], off
	v_add_co_u32_e32 v20, vcc, 0x902d8000, v14
	s_nop 1
	v_addc_co_u32_e32 v21, vcc, 0, v15, vcc
	global_load_dword v109, v[20:21], off
	v_add_co_u32_e32 v20, vcc, 0x902f0000, v14
	s_nop 1
	v_addc_co_u32_e32 v21, vcc, 0, v15, vcc
	global_load_dword v110, v[20:21], off
	v_add_co_u32_e32 v20, vcc, 0x90308000, v14
	s_nop 1
	v_addc_co_u32_e32 v21, vcc, 0, v15, vcc
	global_load_dword v111, v[20:21], off
	v_add_co_u32_e32 v20, vcc, 0x90320000, v14
	s_nop 1
	v_addc_co_u32_e32 v21, vcc, 0, v15, vcc
	global_load_dword v112, v[20:21], off
	v_add_co_u32_e32 v20, vcc, 0x90338000, v14
	s_nop 1
	v_addc_co_u32_e32 v21, vcc, 0, v15, vcc
	global_load_dword v113, v[20:21], off
	v_add_co_u32_e32 v20, vcc, 0x90350000, v14
	s_nop 1
	v_addc_co_u32_e32 v21, vcc, 0, v15, vcc
	v_add_co_u32_e32 v14, vcc, 0x90368000, v14
	global_load_dword v114, v[20:21], off
	s_nop 0
	v_addc_co_u32_e32 v15, vcc, 0, v15, vcc
	global_load_dword v115, v[14:15], off
	s_waitcnt vmcnt(15)
	v_fmac_f32_e32 v19, v100, v100
	s_waitcnt vmcnt(14)
	v_fmac_f32_e32 v19, v101, v101
	s_waitcnt vmcnt(13)
	v_fmac_f32_e32 v19, v102, v102
	s_waitcnt vmcnt(12)
	v_fmac_f32_e32 v19, v103, v103
	s_waitcnt vmcnt(11)
	v_fmac_f32_e32 v19, v104, v104
	s_waitcnt vmcnt(10)
	v_fmac_f32_e32 v19, v105, v105
	s_waitcnt vmcnt(9)
	v_fmac_f32_e32 v19, v106, v106
	s_waitcnt vmcnt(8)
	v_fmac_f32_e32 v19, v107, v107
	s_waitcnt vmcnt(7)
	v_fmac_f32_e32 v19, v108, v108
	s_waitcnt vmcnt(6)
	v_fmac_f32_e32 v19, v109, v109
	s_waitcnt vmcnt(5)
	v_fmac_f32_e32 v19, v110, v110
	s_waitcnt vmcnt(4)
	v_fmac_f32_e32 v19, v111, v111
	s_waitcnt vmcnt(3)
	v_fmac_f32_e32 v19, v112, v112
	s_waitcnt vmcnt(2)
	v_fmac_f32_e32 v19, v113, v113
	s_waitcnt vmcnt(1)
	v_fmac_f32_e32 v19, v114, v114
	s_waitcnt vmcnt(0)
	v_fmac_f32_e32 v19, v115, v115
	s_cbranch_scc0 .LBB0_825
	v_add_u32_e32 v14, s15, v16
	ds_write_b32 v14, v19
	s_waitcnt lgkmcnt(0)
	s_barrier
	ds_read2st64_b32 v[14:15], v16 offset1:1
	s_lshl_b32 s46, s27, 6
	s_ashr_i32 s47, s46, 31
	v_lshl_add_u64 v[12:13], s[46:47], 2, v[4:5]
	v_add_u32_e32 v23, 0x400, v17
	s_waitcnt lgkmcnt(0)
	v_add_f32_e32 v14, 0, v14
	v_add_f32_e32 v19, v14, v15
	ds_read2st64_b32 v[14:15], v16 offset0:2 offset1:3
	v_add_u32_e32 v24, 0x800, v17
	v_add_u32_e32 v33, 0x1400, v17
	v_add_u32_e32 v34, 0x1800, v17
	v_add_u32_e32 v31, 0x1c00, v17
	s_waitcnt lgkmcnt(0)
	v_add_f32_e32 v14, v19, v14
	v_add_f32_e32 v19, v14, v15
	ds_read2st64_b32 v[14:15], v16 offset0:4 offset1:5
	v_add_u32_e32 v32, 0x2000, v17
	v_add_u32_e32 v29, 0x2400, v17
	v_add_u32_e32 v30, 0x2800, v17
	v_add_u32_e32 v27, 0x2c00, v17
	s_waitcnt lgkmcnt(0)
	v_add_f32_e32 v14, v19, v14
	v_add_f32_e32 v19, v14, v15
	ds_read2st64_b32 v[14:15], v16 offset0:6 offset1:7
	v_add_u32_e32 v28, 0x3000, v17
	v_add_u32_e32 v25, 0x3400, v17
	v_add_u32_e32 v26, 0x3800, v17
	s_mov_b32 s51, 1
	s_waitcnt lgkmcnt(0)
	v_add_f32_e32 v14, v19, v14
	v_add_f32_e32 v14, v14, v15
	v_fmamk_f32 v14, v14, 0x3a800000, v214
	v_cmp_gt_f32_e32 vcc, s95, v14
	v_mul_f32_e32 v15, 0x4f800000, v14
	s_mov_b32 s47, s46
	v_cndmask_b32_e32 v14, v14, v15, vcc
	v_sqrt_f32_e32 v15, v14
	s_mov_b32 s50, 0
	v_add_u32_e32 v19, -1, v15
	v_fma_f32 v20, -v19, v15, v14
	v_cmp_ge_f32_e64 s[4:5], 0, v20
	v_add_u32_e32 v20, 1, v15
	s_nop 0
	v_cndmask_b32_e64 v19, v15, v19, s[4:5]
	v_fma_f32 v15, -v20, v15, v14
	v_cmp_lt_f32_e64 s[4:5], 0, v15
	s_nop 1
	v_cndmask_b32_e64 v15, v19, v20, s[4:5]
	v_mul_f32_e32 v19, 0x37800000, v15
	v_cndmask_b32_e32 v15, v15, v19, vcc
	v_cmp_class_f32_e32 vcc, v14, v215
	s_nop 1
	v_cndmask_b32_e32 v14, v15, v14, vcc
	v_div_scale_f32 v15, s[4:5], v14, v14, 1.0
	v_rcp_f32_e32 v19, v15
	s_mov_b32 s5, 0x30000
	s_mov_b32 s4, 0
	v_fma_f32 v20, -v15, v19, 1.0
	v_fmac_f32_e32 v19, v20, v19
	v_div_scale_f32 v20, vcc, 1.0, v14, 1.0
	v_mul_f32_e32 v21, v20, v19
	v_fma_f32 v22, -v15, v21, v20
	v_fmac_f32_e32 v21, v22, v19
	v_fma_f32 v15, -v15, v21, v20
	v_div_fmas_f32 v15, v15, v19, v21
	v_div_fixup_f32 v19, v15, v14, 1.0
	global_load_dword v100, v[12:13], off
	v_add_co_u32_e32 v14, vcc, s72, v12
	s_nop 1
	v_addc_co_u32_e32 v15, vcc, 0, v13, vcc
	global_load_dword v101, v[14:15], off
	v_add_co_u32_e32 v14, vcc, s5, v12
	s_mov_b32 s5, 0x48000
	s_nop 0
	v_addc_co_u32_e32 v15, vcc, 0, v13, vcc
	global_load_dword v102, v[14:15], off
	v_add_co_u32_e32 v14, vcc, s5, v12
	s_mov_b32 s5, 0x60000
; __device__ __forceinline__ void hyena_norm(const float* ZT, const float* gain, bf16* mixed, LAS unsigned char* lds, int vb, int nb, int wave, int lane) {
;     ...
;             for (int cc = 0; cc < 64; ++cc) tile[cc * 65 + lane] = src[(size_t)(cb * 64 + cc) * MTOK] * rstd;
	s_nop 0
	v_addc_co_u32_e32 v15, vcc, 0, v13, vcc
	global_load_dword v103, v[14:15], off
	v_add_co_u32_e32 v14, vcc, s5, v12
	s_mov_b32 s5, 0x78000
	s_nop 0
	v_addc_co_u32_e32 v15, vcc, 0, v13, vcc
	global_load_dword v104, v[14:15], off
	v_add_co_u32_e32 v14, vcc, s5, v12
	s_mov_b32 s5, 0x90000
	s_nop 0
	v_addc_co_u32_e32 v15, vcc, 0, v13, vcc
	global_load_dword v105, v[14:15], off
	v_add_co_u32_e32 v14, vcc, s5, v12
	s_mov_b32 s5, 0xa8000
	s_nop 0
	v_addc_co_u32_e32 v15, vcc, 0, v13, vcc
	global_load_dword v106, v[14:15], off
	v_add_co_u32_e32 v14, vcc, s5, v12
	s_mov_b32 s5, 0xc0000
	s_nop 0
	v_addc_co_u32_e32 v15, vcc, 0, v13, vcc
	global_load_dword v107, v[14:15], off
	v_add_co_u32_e32 v14, vcc, s5, v12
	s_mov_b32 s5, 0xd8000
	s_nop 0
	v_addc_co_u32_e32 v15, vcc, 0, v13, vcc
	global_load_dword v108, v[14:15], off
	v_add_co_u32_e32 v14, vcc, s5, v12
	s_mov_b32 s5, 0xf0000
	s_nop 0
	v_addc_co_u32_e32 v15, vcc, 0, v13, vcc
	global_load_dword v109, v[14:15], off
	v_add_co_u32_e32 v14, vcc, s5, v12
	s_mov_b32 s5, 0x108000
	s_nop 0
	v_addc_co_u32_e32 v15, vcc, 0, v13, vcc
	global_load_dword v110, v[14:15], off
	v_add_co_u32_e32 v14, vcc, s5, v12
	s_mov_b32 s5, 0x120000
	s_nop 0
	v_addc_co_u32_e32 v15, vcc, 0, v13, vcc
	global_load_dword v111, v[14:15], off
	v_add_co_u32_e32 v14, vcc, s5, v12
	s_mov_b32 s5, 0x138000
	s_nop 0
	v_addc_co_u32_e32 v15, vcc, 0, v13, vcc
	global_load_dword v112, v[14:15], off
	v_add_co_u32_e32 v14, vcc, s5, v12
	s_mov_b32 s5, 0x150000
	s_nop 0
	v_addc_co_u32_e32 v15, vcc, 0, v13, vcc
	global_load_dword v113, v[14:15], off
	v_add_co_u32_e32 v14, vcc, s5, v12
	s_mov_b32 s5, 0x168000
	s_nop 0
	v_addc_co_u32_e32 v15, vcc, 0, v13, vcc
	global_load_dword v114, v[14:15], off
	v_add_co_u32_e32 v14, vcc, s5, v12
	s_mov_b32 s5, 0x180000
	s_nop 0
	v_addc_co_u32_e32 v15, vcc, 0, v13, vcc
	global_load_dword v115, v[14:15], off
	v_add_u32_e32 v21, 0xc00, v17
	v_add_u32_e32 v22, 0x1000, v17
	s_waitcnt vmcnt(15)
	v_mul_f32_e32 v20, v100, v19
	s_waitcnt vmcnt(14)
	v_mul_f32_e32 v14, v101, v19
	ds_write2_b32 v17, v20, v14 offset1:65
	s_waitcnt vmcnt(13)
	v_mul_f32_e32 v20, v19, v102
	s_waitcnt vmcnt(12)
	v_mul_f32_e32 v14, v19, v103
	ds_write2_b32 v17, v20, v14 offset0:130 offset1:195
	s_waitcnt vmcnt(11)
	v_mul_f32_e32 v20, v19, v104
	s_waitcnt vmcnt(10)
	v_mul_f32_e32 v14, v19, v105
	ds_write2_b32 v23, v20, v14 offset0:4 offset1:69
	s_waitcnt vmcnt(9)
	v_mul_f32_e32 v20, v19, v106
	s_waitcnt vmcnt(8)
	v_mul_f32_e32 v14, v19, v107
	ds_write2_b32 v23, v20, v14 offset0:134 offset1:199
	s_waitcnt vmcnt(7)
	v_mul_f32_e32 v20, v19, v108
	s_waitcnt vmcnt(6)
	v_mul_f32_e32 v14, v19, v109
	ds_write2_b32 v24, v20, v14 offset0:8 offset1:73
	s_waitcnt vmcnt(5)
	v_mul_f32_e32 v20, v19, v110
	s_waitcnt vmcnt(4)
	v_mul_f32_e32 v14, v19, v111
	ds_write2_b32 v24, v20, v14 offset0:138 offset1:203
	s_waitcnt vmcnt(3)
	v_mul_f32_e32 v20, v19, v112
	s_waitcnt vmcnt(2)
	v_mul_f32_e32 v14, v19, v113
	ds_write2_b32 v21, v20, v14 offset0:12 offset1:77
	s_waitcnt vmcnt(1)
	v_mul_f32_e32 v20, v19, v114
	s_waitcnt vmcnt(0)
	v_mul_f32_e32 v14, v19, v115
	ds_write2_b32 v21, v20, v14 offset0:142 offset1:207
	v_add_co_u32_e32 v14, vcc, s5, v12
	s_mov_b32 s5, 0x198000
	s_nop 0
	v_addc_co_u32_e32 v15, vcc, 0, v13, vcc
	global_load_dword v100, v[14:15], off
	v_add_co_u32_e32 v14, vcc, s5, v12
	s_mov_b32 s5, 0x1b0000
	s_nop 0
	v_addc_co_u32_e32 v15, vcc, 0, v13, vcc
	global_load_dword v101, v[14:15], off
	v_add_co_u32_e32 v14, vcc, s5, v12
	s_mov_b32 s5, 0x1c8000
	s_nop 0
	v_addc_co_u32_e32 v15, vcc, 0, v13, vcc
	global_load_dword v102, v[14:15], off
	v_add_co_u32_e32 v14, vcc, s5, v12
	s_mov_b32 s5, 0x1e0000
	s_nop 0
	v_addc_co_u32_e32 v15, vcc, 0, v13, vcc
	global_load_dword v103, v[14:15], off
	v_add_co_u32_e32 v14, vcc, s5, v12
	s_mov_b32 s5, 0x1f8000
	s_nop 0
	v_addc_co_u32_e32 v15, vcc, 0, v13, vcc
	global_load_dword v104, v[14:15], off
	v_add_co_u32_e32 v14, vcc, s5, v12
	s_mov_b32 s5, 0x210000
	s_nop 0
	v_addc_co_u32_e32 v15, vcc, 0, v13, vcc
	global_load_dword v105, v[14:15], off
	v_add_co_u32_e32 v14, vcc, s5, v12
	s_mov_b32 s5, 0x228000
	s_nop 0
	v_addc_co_u32_e32 v15, vcc, 0, v13, vcc
	global_load_dword v106, v[14:15], off
	v_add_co_u32_e32 v14, vcc, s5, v12
	s_mov_b32 s5, 0x240000
	s_nop 0
	v_addc_co_u32_e32 v15, vcc, 0, v13, vcc
	global_load_dword v107, v[14:15], off
	v_add_co_u32_e32 v14, vcc, s5, v12
	s_mov_b32 s5, 0x258000
	s_nop 0
	v_addc_co_u32_e32 v15, vcc, 0, v13, vcc
	global_load_dword v108, v[14:15], off
	v_add_co_u32_e32 v14, vcc, s5, v12
	s_mov_b32 s5, 0x270000
	s_nop 0
	v_addc_co_u32_e32 v15, vcc, 0, v13, vcc
	global_load_dword v109, v[14:15], off
	v_add_co_u32_e32 v14, vcc, s5, v12
	s_mov_b32 s5, 0x288000
	s_nop 0
	v_addc_co_u32_e32 v15, vcc, 0, v13, vcc
	global_load_dword v110, v[14:15], off
	v_add_co_u32_e32 v14, vcc, s5, v12
	s_mov_b32 s5, 0x2a0000
	s_nop 0
	v_addc_co_u32_e32 v15, vcc, 0, v13, vcc
	global_load_dword v111, v[14:15], off
	v_add_co_u32_e32 v14, vcc, s5, v12
	s_mov_b32 s5, 0x2b8000
	s_nop 0
	v_addc_co_u32_e32 v15, vcc, 0, v13, vcc
	global_load_dword v112, v[14:15], off
	v_add_co_u32_e32 v14, vcc, s5, v12
	s_mov_b32 s5, 0x2d0000
	s_nop 0
	v_addc_co_u32_e32 v15, vcc, 0, v13, vcc
	global_load_dword v113, v[14:15], off
	v_add_co_u32_e32 v14, vcc, s5, v12
	s_mov_b32 s5, 0x2e8000
	s_nop 0
	v_addc_co_u32_e32 v15, vcc, 0, v13, vcc
	global_load_dword v114, v[14:15], off
	v_add_co_u32_e32 v14, vcc, s5, v12
	s_mov_b32 s5, 0x300000
	s_nop 0
	v_addc_co_u32_e32 v15, vcc, 0, v13, vcc
	global_load_dword v115, v[14:15], off
	s_waitcnt vmcnt(15)
	v_mul_f32_e32 v20, v19, v100
	s_waitcnt vmcnt(14)
; __device__ __forceinline__ void hyena_norm(const float* ZT, const float* gain, bf16* mixed, LAS unsigned char* lds, int vb, int nb, int wave, int lane) {
;     ...
;             for (int cc = 0; cc < 64; ++cc) tile[cc * 65 + lane] = src[(size_t)(cb * 64 + cc) * MTOK] * rstd;
	v_mul_f32_e32 v14, v19, v101
	ds_write2_b32 v22, v20, v14 offset0:16 offset1:81
	s_waitcnt vmcnt(13)
	v_mul_f32_e32 v20, v19, v102
	s_waitcnt vmcnt(12)
	v_mul_f32_e32 v14, v19, v103
	ds_write2_b32 v22, v20, v14 offset0:146 offset1:211
	s_waitcnt vmcnt(11)
	v_mul_f32_e32 v20, v19, v104
	s_waitcnt vmcnt(10)
	v_mul_f32_e32 v14, v19, v105
	ds_write2_b32 v33, v20, v14 offset0:20 offset1:85
	s_waitcnt vmcnt(9)
	v_mul_f32_e32 v20, v19, v106
	s_waitcnt vmcnt(8)
	v_mul_f32_e32 v14, v19, v107
	ds_write2_b32 v33, v20, v14 offset0:150 offset1:215
	s_waitcnt vmcnt(7)
	v_mul_f32_e32 v20, v19, v108
	s_waitcnt vmcnt(6)
	v_mul_f32_e32 v14, v19, v109
	ds_write2_b32 v34, v20, v14 offset0:24 offset1:89
	s_waitcnt vmcnt(5)
	v_mul_f32_e32 v20, v19, v110
	s_waitcnt vmcnt(4)
	v_mul_f32_e32 v14, v19, v111
	ds_write2_b32 v34, v20, v14 offset0:154 offset1:219
	s_waitcnt vmcnt(3)
	v_mul_f32_e32 v20, v19, v112
	s_waitcnt vmcnt(2)
	v_mul_f32_e32 v14, v19, v113
	ds_write2_b32 v31, v20, v14 offset0:28 offset1:93
	s_waitcnt vmcnt(1)
	v_mul_f32_e32 v20, v19, v114
	s_waitcnt vmcnt(0)
	v_mul_f32_e32 v14, v19, v115
	ds_write2_b32 v31, v20, v14 offset0:158 offset1:223
	v_add_co_u32_e32 v14, vcc, s5, v12
	s_mov_b32 s5, 0x318000
	s_nop 0
	v_addc_co_u32_e32 v15, vcc, 0, v13, vcc
	global_load_dword v100, v[14:15], off
	v_add_co_u32_e32 v14, vcc, s5, v12
	s_mov_b32 s5, 0x330000
	s_nop 0
	v_addc_co_u32_e32 v15, vcc, 0, v13, vcc
	global_load_dword v101, v[14:15], off
	v_add_co_u32_e32 v14, vcc, s5, v12
	s_mov_b32 s5, 0x348000
	s_nop 0
	v_addc_co_u32_e32 v15, vcc, 0, v13, vcc
	global_load_dword v102, v[14:15], off
	v_add_co_u32_e32 v14, vcc, s5, v12
	s_mov_b32 s5, 0x360000
	s_nop 0
	v_addc_co_u32_e32 v15, vcc, 0, v13, vcc
	global_load_dword v103, v[14:15], off
	v_add_co_u32_e32 v14, vcc, s5, v12
	s_mov_b32 s5, 0x378000
	s_nop 0
	v_addc_co_u32_e32 v15, vcc, 0, v13, vcc
	global_load_dword v104, v[14:15], off
	v_add_co_u32_e32 v14, vcc, s5, v12
	s_mov_b32 s5, 0x390000
	s_nop 0
	v_addc_co_u32_e32 v15, vcc, 0, v13, vcc
	global_load_dword v105, v[14:15], off
	v_add_co_u32_e32 v14, vcc, s5, v12
	s_mov_b32 s5, 0x3a8000
	s_nop 0
	v_addc_co_u32_e32 v15, vcc, 0, v13, vcc
	global_load_dword v106, v[14:15], off
	v_add_co_u32_e32 v14, vcc, s5, v12
	s_mov_b32 s5, 0x3c0000
	s_nop 0
	v_addc_co_u32_e32 v15, vcc, 0, v13, vcc
	global_load_dword v107, v[14:15], off
	v_add_co_u32_e32 v14, vcc, s5, v12
	s_mov_b32 s5, 0x3d8000
	s_nop 0
	v_addc_co_u32_e32 v15, vcc, 0, v13, vcc
	global_load_dword v108, v[14:15], off
	v_add_co_u32_e32 v14, vcc, s5, v12
	s_mov_b32 s5, 0x3f0000
	s_nop 0
	v_addc_co_u32_e32 v15, vcc, 0, v13, vcc
	global_load_dword v109, v[14:15], off
	v_add_co_u32_e32 v14, vcc, s5, v12
	s_mov_b32 s5, 0x408000
	s_nop 0
	v_addc_co_u32_e32 v15, vcc, 0, v13, vcc
	global_load_dword v110, v[14:15], off
	v_add_co_u32_e32 v14, vcc, s5, v12
	s_mov_b32 s5, 0x420000
	s_nop 0
	v_addc_co_u32_e32 v15, vcc, 0, v13, vcc
	global_load_dword v111, v[14:15], off
	v_add_co_u32_e32 v14, vcc, s5, v12
	s_mov_b32 s5, 0x438000
	s_nop 0
	v_addc_co_u32_e32 v15, vcc, 0, v13, vcc
	global_load_dword v112, v[14:15], off
	v_add_co_u32_e32 v14, vcc, s5, v12
	s_mov_b32 s5, 0x450000
	s_nop 0
	v_addc_co_u32_e32 v15, vcc, 0, v13, vcc
	global_load_dword v113, v[14:15], off
	v_add_co_u32_e32 v14, vcc, s5, v12
	s_mov_b32 s5, 0x468000
	s_nop 0
	v_addc_co_u32_e32 v15, vcc, 0, v13, vcc
	global_load_dword v114, v[14:15], off
	v_add_co_u32_e32 v14, vcc, s5, v12
	s_mov_b32 s5, 0x480000
	s_nop 0
	v_addc_co_u32_e32 v15, vcc, 0, v13, vcc
	global_load_dword v115, v[14:15], off
	s_waitcnt vmcnt(15)
	v_mul_f32_e32 v20, v19, v100
	s_waitcnt vmcnt(14)
	v_mul_f32_e32 v14, v19, v101
	ds_write2_b32 v32, v20, v14 offset0:32 offset1:97
	s_waitcnt vmcnt(13)
	v_mul_f32_e32 v20, v19, v102
	s_waitcnt vmcnt(12)
	v_mul_f32_e32 v14, v19, v103
	ds_write2_b32 v32, v20, v14 offset0:162 offset1:227
	s_waitcnt vmcnt(11)
	v_mul_f32_e32 v20, v19, v104
	s_waitcnt vmcnt(10)
	v_mul_f32_e32 v14, v19, v105
	ds_write2_b32 v29, v20, v14 offset0:36 offset1:101
	s_waitcnt vmcnt(9)
	v_mul_f32_e32 v20, v19, v106
	s_waitcnt vmcnt(8)
	v_mul_f32_e32 v14, v19, v107
	ds_write2_b32 v29, v20, v14 offset0:166 offset1:231
	s_waitcnt vmcnt(7)
	v_mul_f32_e32 v20, v19, v108
	s_waitcnt vmcnt(6)
	v_mul_f32_e32 v14, v19, v109
	ds_write2_b32 v30, v20, v14 offset0:40 offset1:105
	s_waitcnt vmcnt(5)
	v_mul_f32_e32 v20, v19, v110
	s_waitcnt vmcnt(4)
	v_mul_f32_e32 v14, v19, v111
	ds_write2_b32 v30, v20, v14 offset0:170 offset1:235
	s_waitcnt vmcnt(3)
	v_mul_f32_e32 v20, v19, v112
	s_waitcnt vmcnt(2)
	v_mul_f32_e32 v14, v19, v113
	ds_write2_b32 v27, v20, v14 offset0:44 offset1:109
	s_waitcnt vmcnt(1)
	v_mul_f32_e32 v20, v19, v114
	s_waitcnt vmcnt(0)
; __device__ __forceinline__ unsigned f2bf(float f) { unsigned u = __builtin_bit_cast(unsigned, f); return (u + 0x7fffu + ((u >> 16) & 1u)) >> 16; }
; #define LDS_WAIT() asm volatile("s_waitcnt lgkmcnt(0)" ::: "memory")
; __device__ __forceinline__ void hyena_norm(const float* ZT, const float* gain, bf16* mixed, LAS unsigned char* lds, int vb, int nb, int wave, int lane) {
;     ...
;             for (int cc = 0; cc < 64; ++cc) tile[cc * 65 + lane] = src[(size_t)(cb * 64 + cc) * MTOK] * rstd;
;             LDS_WAIT();
;             const float gv = gain[c0 + lane];
;             for (int i = 0; i < 64; ++i) mixed[(size_t)(R0 + i) * DM + 1024 + c0 + lane] = (bf16)f2bf(tile[lane * 65 + i] * gv);
	v_mul_f32_e32 v14, v19, v115
	ds_write2_b32 v27, v20, v14 offset0:174 offset1:239
	v_add_co_u32_e32 v14, vcc, s5, v12
	s_mov_b32 s5, 0x498000
	s_nop 0
	v_addc_co_u32_e32 v15, vcc, 0, v13, vcc
	global_load_dword v100, v[14:15], off
	v_add_co_u32_e32 v14, vcc, s5, v12
	s_mov_b32 s5, 0x4b0000
	s_nop 0
	v_addc_co_u32_e32 v15, vcc, 0, v13, vcc
	global_load_dword v101, v[14:15], off
	v_add_co_u32_e32 v14, vcc, s5, v12
	s_mov_b32 s5, 0x4c8000
	s_nop 0
	v_addc_co_u32_e32 v15, vcc, 0, v13, vcc
	global_load_dword v102, v[14:15], off
	v_add_co_u32_e32 v14, vcc, s5, v12
	s_mov_b32 s5, 0x4e0000
	s_nop 0
	v_addc_co_u32_e32 v15, vcc, 0, v13, vcc
	global_load_dword v103, v[14:15], off
	v_add_co_u32_e32 v14, vcc, s5, v12
	s_mov_b32 s5, 0x4f8000
	s_nop 0
	v_addc_co_u32_e32 v15, vcc, 0, v13, vcc
	global_load_dword v104, v[14:15], off
	v_add_co_u32_e32 v14, vcc, s5, v12
	s_mov_b32 s5, 0x510000
	s_nop 0
	v_addc_co_u32_e32 v15, vcc, 0, v13, vcc
	global_load_dword v105, v[14:15], off
	v_add_co_u32_e32 v14, vcc, s5, v12
	s_mov_b32 s5, 0x528000
	s_nop 0
	v_addc_co_u32_e32 v15, vcc, 0, v13, vcc
	global_load_dword v106, v[14:15], off
	v_add_co_u32_e32 v14, vcc, s5, v12
	s_mov_b32 s5, 0x540000
	s_nop 0
	v_addc_co_u32_e32 v15, vcc, 0, v13, vcc
	global_load_dword v107, v[14:15], off
	v_add_co_u32_e32 v14, vcc, s5, v12
	s_mov_b32 s5, 0x558000
	s_nop 0
	v_addc_co_u32_e32 v15, vcc, 0, v13, vcc
	global_load_dword v108, v[14:15], off
	v_add_co_u32_e32 v14, vcc, s5, v12
	s_mov_b32 s5, 0x570000
	s_nop 0
	v_addc_co_u32_e32 v15, vcc, 0, v13, vcc
	global_load_dword v109, v[14:15], off
	v_add_co_u32_e32 v14, vcc, s5, v12
	s_mov_b32 s5, 0x588000
	s_nop 0
	v_addc_co_u32_e32 v15, vcc, 0, v13, vcc
	global_load_dword v110, v[14:15], off
	v_add_co_u32_e32 v14, vcc, s5, v12
	s_mov_b32 s5, 0x5a0000
	s_nop 0
	v_addc_co_u32_e32 v15, vcc, 0, v13, vcc
	global_load_dword v111, v[14:15], off
	v_add_co_u32_e32 v14, vcc, s5, v12
	s_mov_b32 s5, 0x5b8000
	s_nop 0
	v_addc_co_u32_e32 v15, vcc, 0, v13, vcc
	global_load_dword v112, v[14:15], off
	v_add_co_u32_e32 v14, vcc, s5, v12
	s_mov_b32 s5, 0x5d0000
	s_nop 0
	v_addc_co_u32_e32 v15, vcc, 0, v13, vcc
	global_load_dword v113, v[14:15], off
	v_add_co_u32_e32 v14, vcc, s5, v12
	s_nop 1
	v_addc_co_u32_e32 v15, vcc, 0, v13, vcc
	global_load_dword v114, v[14:15], off
	v_add_co_u32_e32 v14, vcc, 0x5e8000, v12
	s_nop 1
	v_addc_co_u32_e32 v15, vcc, 0, v13, vcc
	global_load_dword v115, v[14:15], off
	s_waitcnt vmcnt(15)
	v_mul_f32_e32 v20, v19, v100
	s_waitcnt vmcnt(14)
	v_mul_f32_e32 v14, v19, v101
	ds_write2_b32 v28, v20, v14 offset0:48 offset1:113
	s_waitcnt vmcnt(13)
	v_mul_f32_e32 v20, v19, v102
	s_waitcnt vmcnt(12)
	v_mul_f32_e32 v14, v19, v103
	ds_write2_b32 v28, v20, v14 offset0:178 offset1:243
	s_waitcnt vmcnt(11)
	v_mul_f32_e32 v20, v19, v104
	s_waitcnt vmcnt(10)
	v_mul_f32_e32 v14, v19, v105
	ds_write2_b32 v25, v20, v14 offset0:52 offset1:117
	s_waitcnt vmcnt(9)
	v_mul_f32_e32 v20, v19, v106
	s_waitcnt vmcnt(8)
	v_mul_f32_e32 v14, v19, v107
	ds_write2_b32 v25, v20, v14 offset0:182 offset1:247
	s_waitcnt vmcnt(7)
	v_mul_f32_e32 v20, v19, v108
	s_waitcnt vmcnt(6)
	v_mul_f32_e32 v14, v19, v109
	ds_write2_b32 v26, v20, v14 offset0:56 offset1:121
	s_waitcnt vmcnt(5)
	v_mul_f32_e32 v20, v19, v110
	s_waitcnt vmcnt(4)
	v_mul_f32_e32 v14, v19, v111
	ds_write2_b32 v26, v20, v14 offset0:186 offset1:251
	v_add_u32_e32 v20, 0x3c00, v17
	s_waitcnt vmcnt(3)
	v_mul_f32_e32 v35, v19, v112
	s_waitcnt vmcnt(2)
	v_mul_f32_e32 v14, v19, v113
	ds_write2_b32 v20, v35, v14 offset0:60 offset1:125
	s_waitcnt vmcnt(1)
	v_mul_f32_e32 v35, v19, v114
	s_waitcnt vmcnt(0)
	v_mul_f32_e32 v14, v19, v115
	ds_write2_b32 v20, v35, v14 offset0:190 offset1:255
	s_waitcnt lgkmcnt(0)
	global_load_dword v14, v[6:7], off
	s_waitcnt vmcnt(0)
	v_mov_b32_e32 v15, v14
.LBB0_827:
	v_add_u32_e32 v35, s4, v18
	ds_read2_b32 v[36:37], v35 offset1:1
	s_or_b64 s[28:29], s[50:51], s[46:47]
	s_ashr_i32 s31, s28, 31
	s_mov_b32 s30, s28
	s_ashr_i32 s45, s29, 31
	s_waitcnt lgkmcnt(0)
	v_pk_mul_f32 v[36:37], v[14:15], v[36:37]
	s_mov_b32 s44, s29
	v_and_b32_sdwa v38, v37, v212 dst_sel:DWORD dst_unused:UNUSED_PAD src0_sel:WORD_1 src1_sel:DWORD
	v_and_b32_sdwa v39, v36, v212 dst_sel:DWORD dst_unused:UNUSED_PAD src0_sel:WORD_1 src1_sel:DWORD
	s_lshl_b64 s[30:31], s[30:31], 13
	v_add3_u32 v40, v37, v38, s13
	v_add3_u32 v41, v36, v39, s13
	s_lshl_b64 s[28:29], s[44:45], 13
	v_lshl_add_u64 v[36:37], v[10:11], 0, s[30:31]
	v_lshl_add_u64 v[38:39], v[10:11], 0, s[28:29]
	global_store_short_d16_hi v[36:37], v41, off offset:2048
	global_store_short_d16_hi v[38:39], v40, off offset:2048
	ds_read2_b32 v[36:37], v35 offset0:2 offset1:3
	s_add_i32 s37, s50, s46
	s_add_i32 s5, s51, s47
	s_add_i32 s30, s37, 2
	s_add_i32 s28, s5, 2
	s_waitcnt lgkmcnt(0)
	v_pk_mul_f32 v[36:37], v[14:15], v[36:37]
	s_ashr_i32 s31, s30, 31
	v_and_b32_sdwa v38, v37, v212 dst_sel:DWORD dst_unused:UNUSED_PAD src0_sel:WORD_1 src1_sel:DWORD
	v_and_b32_sdwa v39, v36, v212 dst_sel:DWORD dst_unused:UNUSED_PAD src0_sel:WORD_1 src1_sel:DWORD
	s_ashr_i32 s29, s28, 31
	s_lshl_b64 s[30:31], s[30:31], 13
	v_add3_u32 v40, v37, v38, s13
	v_add3_u32 v41, v36, v39, s13
	s_lshl_b64 s[28:29], s[28:29], 13
	v_lshl_add_u64 v[36:37], v[10:11], 0, s[30:31]
	v_lshl_add_u64 v[38:39], v[10:11], 0, s[28:29]
	global_store_short_d16_hi v[36:37], v41, off offset:2048
	global_store_short_d16_hi v[38:39], v40, off offset:2048
	ds_read2_b32 v[36:37], v35 offset0:4 offset1:5
	s_add_i32 s30, s37, 4
	s_add_i32 s28, s5, 4
	s_ashr_i32 s31, s30, 31
	s_ashr_i32 s29, s28, 31
	s_waitcnt lgkmcnt(0)
	v_pk_mul_f32 v[36:37], v[14:15], v[36:37]
	s_lshl_b64 s[30:31], s[30:31], 13
	v_and_b32_sdwa v38, v37, v212 dst_sel:DWORD dst_unused:UNUSED_PAD src0_sel:WORD_1 src1_sel:DWORD
	v_and_b32_sdwa v39, v36, v212 dst_sel:DWORD dst_unused:UNUSED_PAD src0_sel:WORD_1 src1_sel:DWORD
	v_add3_u32 v40, v37, v38, s13
	v_add3_u32 v41, v36, v39, s13
	s_lshl_b64 s[28:29], s[28:29], 13
	v_lshl_add_u64 v[36:37], v[10:11], 0, s[30:31]
	v_lshl_add_u64 v[38:39], v[10:11], 0, s[28:29]
	global_store_short_d16_hi v[36:37], v41, off offset:2048
	global_store_short_d16_hi v[38:39], v40, off offset:2048
	ds_read2_b32 v[36:37], v35 offset0:6 offset1:7
	s_add_i32 s28, s5, 6
	s_add_i32 s30, s37, 6
	s_ashr_i32 s31, s30, 31
	s_ashr_i32 s29, s28, 31
	s_waitcnt lgkmcnt(0)
	v_pk_mul_f32 v[36:37], v[14:15], v[36:37]
	s_lshl_b64 s[28:29], s[28:29], 13
	v_and_b32_sdwa v35, v37, v212 dst_sel:DWORD dst_unused:UNUSED_PAD src0_sel:WORD_1 src1_sel:DWORD
	v_and_b32_sdwa v38, v36, v212 dst_sel:DWORD dst_unused:UNUSED_PAD src0_sel:WORD_1 src1_sel:DWORD
	s_lshl_b64 s[30:31], s[30:31], 13
	s_add_i32 s50, s50, 8
	s_add_i32 s51, s51, 8
	s_add_i32 s4, s4, 32
	v_add3_u32 v35, v37, v35, s13
	v_add3_u32 v40, v36, v38, s13
	v_lshl_add_u64 v[36:37], v[10:11], 0, s[30:31]
	s_cmpk_eq_i32 s4, 0x100
	v_lshl_add_u64 v[38:39], v[10:11], 0, s[28:29]
	global_store_short_d16_hi v[36:37], v40, off offset:2048
	global_store_short_d16_hi v[38:39], v35, off offset:2048
	s_cbranch_scc0 .LBB0_827
; __device__ __forceinline__ unsigned f2bf(float f) { unsigned u = __builtin_bit_cast(unsigned, f); return (u + 0x7fffu + ((u >> 16) & 1u)) >> 16; }
; #define LDS_WAIT() asm volatile("s_waitcnt lgkmcnt(0)" ::: "memory")
; __device__ __forceinline__ void hyena_norm(const float* ZT, const float* gain, bf16* mixed, LAS unsigned char* lds, int vb, int nb, int wave, int lane) {
;     ...
;             for (int cc = 0; cc < 64; ++cc) tile[cc * 65 + lane] = src[(size_t)(cb * 64 + cc) * MTOK] * rstd;
;             LDS_WAIT();
;             const float gv = gain[c0 + lane];
;             for (int i = 0; i < 64; ++i) mixed[(size_t)(R0 + i) * DM + 1024 + c0 + lane] = (bf16)f2bf(tile[lane * 65 + i] * gv);
;             LDS_WAIT();
	v_add_co_u32_e32 v14, vcc, 0x600000, v12
	s_mov_b32 s28, 0
	s_nop 0
	v_addc_co_u32_e32 v15, vcc, 0, v13, vcc
	global_load_dword v100, v[14:15], off
	s_mov_b32 s5, 1
	s_mov_b32 s4, 0
	v_add_co_u32_e32 v14, vcc, 0x618000, v12
	s_nop 1
	v_addc_co_u32_e32 v15, vcc, 0, v13, vcc
	global_load_dword v101, v[14:15], off
	v_add_co_u32_e32 v14, vcc, 0x630000, v12
	s_nop 1
	v_addc_co_u32_e32 v15, vcc, 0, v13, vcc
	global_load_dword v102, v[14:15], off
	v_add_co_u32_e32 v14, vcc, 0x648000, v12
	s_nop 1
	v_addc_co_u32_e32 v15, vcc, 0, v13, vcc
	global_load_dword v103, v[14:15], off
	v_add_co_u32_e32 v14, vcc, 0x660000, v12
	s_nop 1
	v_addc_co_u32_e32 v15, vcc, 0, v13, vcc
	global_load_dword v104, v[14:15], off
	v_add_co_u32_e32 v14, vcc, 0x678000, v12
	s_nop 1
	v_addc_co_u32_e32 v15, vcc, 0, v13, vcc
	global_load_dword v105, v[14:15], off
	v_add_co_u32_e32 v14, vcc, 0x690000, v12
	s_nop 1
	v_addc_co_u32_e32 v15, vcc, 0, v13, vcc
	global_load_dword v106, v[14:15], off
	v_add_co_u32_e32 v14, vcc, 0x6a8000, v12
	s_nop 1
	v_addc_co_u32_e32 v15, vcc, 0, v13, vcc
	global_load_dword v107, v[14:15], off
	v_add_co_u32_e32 v14, vcc, 0x6c0000, v12
	s_nop 1
	v_addc_co_u32_e32 v15, vcc, 0, v13, vcc
	global_load_dword v108, v[14:15], off
	v_add_co_u32_e32 v14, vcc, 0x6d8000, v12
	s_nop 1
	v_addc_co_u32_e32 v15, vcc, 0, v13, vcc
	global_load_dword v109, v[14:15], off
	v_add_co_u32_e32 v14, vcc, 0x6f0000, v12
	s_nop 1
	v_addc_co_u32_e32 v15, vcc, 0, v13, vcc
	global_load_dword v110, v[14:15], off
	v_add_co_u32_e32 v14, vcc, 0x708000, v12
	s_nop 1
	v_addc_co_u32_e32 v15, vcc, 0, v13, vcc
	global_load_dword v111, v[14:15], off
	v_add_co_u32_e32 v14, vcc, 0x720000, v12
	s_nop 1
	v_addc_co_u32_e32 v15, vcc, 0, v13, vcc
	global_load_dword v112, v[14:15], off
	v_add_co_u32_e32 v14, vcc, 0x738000, v12
	s_nop 1
	v_addc_co_u32_e32 v15, vcc, 0, v13, vcc
	global_load_dword v113, v[14:15], off
	v_add_co_u32_e32 v14, vcc, 0x750000, v12
	s_nop 1
	v_addc_co_u32_e32 v15, vcc, 0, v13, vcc
	global_load_dword v114, v[14:15], off
	v_add_co_u32_e32 v14, vcc, 0x768000, v12
	s_nop 1
	v_addc_co_u32_e32 v15, vcc, 0, v13, vcc
	global_load_dword v115, v[14:15], off
	s_waitcnt lgkmcnt(0)
	s_waitcnt vmcnt(15)
	v_mul_f32_e32 v35, v19, v100
	s_waitcnt vmcnt(14)
	v_mul_f32_e32 v14, v19, v101
	ds_write2_b32 v17, v35, v14 offset1:65
	s_waitcnt vmcnt(13)
	v_mul_f32_e32 v35, v19, v102
	s_waitcnt vmcnt(12)
	v_mul_f32_e32 v14, v19, v103
	ds_write2_b32 v17, v35, v14 offset0:130 offset1:195
	s_waitcnt vmcnt(11)
	v_mul_f32_e32 v35, v19, v104
	s_waitcnt vmcnt(10)
	v_mul_f32_e32 v14, v19, v105
	ds_write2_b32 v23, v35, v14 offset0:4 offset1:69
	s_waitcnt vmcnt(9)
	v_mul_f32_e32 v35, v19, v106
	s_waitcnt vmcnt(8)
	v_mul_f32_e32 v14, v19, v107
	ds_write2_b32 v23, v35, v14 offset0:134 offset1:199
	s_waitcnt vmcnt(7)
	v_mul_f32_e32 v23, v19, v108
	s_waitcnt vmcnt(6)
	v_mul_f32_e32 v14, v19, v109
	ds_write2_b32 v24, v23, v14 offset0:8 offset1:73
	s_waitcnt vmcnt(5)
	v_mul_f32_e32 v23, v19, v110
	s_waitcnt vmcnt(4)
	v_mul_f32_e32 v14, v19, v111
	ds_write2_b32 v24, v23, v14 offset0:138 offset1:203
	s_waitcnt vmcnt(3)
	v_mul_f32_e32 v23, v19, v112
	s_waitcnt vmcnt(2)
	v_mul_f32_e32 v14, v19, v113
	ds_write2_b32 v21, v23, v14 offset0:12 offset1:77
	s_waitcnt vmcnt(1)
	v_mul_f32_e32 v23, v19, v114
	s_waitcnt vmcnt(0)
	v_mul_f32_e32 v14, v19, v115
	ds_write2_b32 v21, v23, v14 offset0:142 offset1:207
	v_add_co_u32_e32 v14, vcc, 0x780000, v12
	s_nop 1
	v_addc_co_u32_e32 v15, vcc, 0, v13, vcc
	global_load_dword v100, v[14:15], off
	v_add_co_u32_e32 v14, vcc, 0x798000, v12
	s_nop 1
	v_addc_co_u32_e32 v15, vcc, 0, v13, vcc
	global_load_dword v101, v[14:15], off
	v_add_co_u32_e32 v14, vcc, 0x7b0000, v12
	s_nop 1
	v_addc_co_u32_e32 v15, vcc, 0, v13, vcc
	global_load_dword v102, v[14:15], off
	v_add_co_u32_e32 v14, vcc, 0x7c8000, v12
	s_nop 1
	v_addc_co_u32_e32 v15, vcc, 0, v13, vcc
	global_load_dword v103, v[14:15], off
	v_add_co_u32_e32 v14, vcc, 0x7e0000, v12
	s_nop 1
	v_addc_co_u32_e32 v15, vcc, 0, v13, vcc
	global_load_dword v104, v[14:15], off
	v_add_co_u32_e32 v14, vcc, 0x7f8000, v12
	s_nop 1
	v_addc_co_u32_e32 v15, vcc, 0, v13, vcc
	global_load_dword v105, v[14:15], off
	v_add_co_u32_e32 v14, vcc, 0x810000, v12
	s_nop 1
	v_addc_co_u32_e32 v15, vcc, 0, v13, vcc
	global_load_dword v106, v[14:15], off
	v_add_co_u32_e32 v14, vcc, 0x828000, v12
	s_nop 1
	v_addc_co_u32_e32 v15, vcc, 0, v13, vcc
	global_load_dword v107, v[14:15], off
	v_add_co_u32_e32 v14, vcc, 0x840000, v12
	s_nop 1
	v_addc_co_u32_e32 v15, vcc, 0, v13, vcc
	global_load_dword v108, v[14:15], off
	v_add_co_u32_e32 v14, vcc, 0x858000, v12
	s_nop 1
	v_addc_co_u32_e32 v15, vcc, 0, v13, vcc
	global_load_dword v109, v[14:15], off
	v_add_co_u32_e32 v14, vcc, 0x870000, v12
	s_nop 1
	v_addc_co_u32_e32 v15, vcc, 0, v13, vcc
	global_load_dword v110, v[14:15], off
	v_add_co_u32_e32 v14, vcc, 0x888000, v12
	s_nop 1
	v_addc_co_u32_e32 v15, vcc, 0, v13, vcc
	global_load_dword v111, v[14:15], off
	v_add_co_u32_e32 v14, vcc, 0x8a0000, v12
	s_nop 1
	v_addc_co_u32_e32 v15, vcc, 0, v13, vcc
	global_load_dword v112, v[14:15], off
	v_add_co_u32_e32 v14, vcc, 0x8b8000, v12
	s_nop 1
	v_addc_co_u32_e32 v15, vcc, 0, v13, vcc
	global_load_dword v113, v[14:15], off
	v_add_co_u32_e32 v14, vcc, 0x8d0000, v12
	s_nop 1
	v_addc_co_u32_e32 v15, vcc, 0, v13, vcc
	global_load_dword v114, v[14:15], off
	v_add_co_u32_e32 v14, vcc, 0x8e8000, v12
	s_nop 1
	v_addc_co_u32_e32 v15, vcc, 0, v13, vcc
	global_load_dword v115, v[14:15], off
	s_waitcnt vmcnt(15)
	v_mul_f32_e32 v21, v19, v100
	s_waitcnt vmcnt(14)
	v_mul_f32_e32 v14, v19, v101
	ds_write2_b32 v22, v21, v14 offset0:16 offset1:81
	s_waitcnt vmcnt(13)
; __device__ __forceinline__ void hyena_norm(const float* ZT, const float* gain, bf16* mixed, LAS unsigned char* lds, int vb, int nb, int wave, int lane) {
;     ...
;             for (int cc = 0; cc < 64; ++cc) tile[cc * 65 + lane] = src[(size_t)(cb * 64 + cc) * MTOK] * rstd;
	v_mul_f32_e32 v21, v19, v102
	s_waitcnt vmcnt(12)
	v_mul_f32_e32 v14, v19, v103
	ds_write2_b32 v22, v21, v14 offset0:146 offset1:211
	s_waitcnt vmcnt(11)
	v_mul_f32_e32 v21, v19, v104
	s_waitcnt vmcnt(10)
	v_mul_f32_e32 v14, v19, v105
	ds_write2_b32 v33, v21, v14 offset0:20 offset1:85
	s_waitcnt vmcnt(9)
	v_mul_f32_e32 v21, v19, v106
	s_waitcnt vmcnt(8)
	v_mul_f32_e32 v14, v19, v107
	ds_write2_b32 v33, v21, v14 offset0:150 offset1:215
	s_waitcnt vmcnt(7)
	v_mul_f32_e32 v21, v19, v108
	s_waitcnt vmcnt(6)
	v_mul_f32_e32 v14, v19, v109
	ds_write2_b32 v34, v21, v14 offset0:24 offset1:89
	s_waitcnt vmcnt(5)
	v_mul_f32_e32 v21, v19, v110
	s_waitcnt vmcnt(4)
	v_mul_f32_e32 v14, v19, v111
	ds_write2_b32 v34, v21, v14 offset0:154 offset1:219
	s_waitcnt vmcnt(3)
	v_mul_f32_e32 v21, v19, v112
	s_waitcnt vmcnt(2)
	v_mul_f32_e32 v14, v19, v113
	ds_write2_b32 v31, v21, v14 offset0:28 offset1:93
	s_waitcnt vmcnt(1)
	v_mul_f32_e32 v21, v19, v114
	s_waitcnt vmcnt(0)
	v_mul_f32_e32 v14, v19, v115
	ds_write2_b32 v31, v21, v14 offset0:158 offset1:223
	v_add_co_u32_e32 v14, vcc, 0x900000, v12
	s_nop 1
	v_addc_co_u32_e32 v15, vcc, 0, v13, vcc
	global_load_dword v100, v[14:15], off
	v_add_co_u32_e32 v14, vcc, 0x918000, v12
	s_nop 1
	v_addc_co_u32_e32 v15, vcc, 0, v13, vcc
	global_load_dword v101, v[14:15], off
	v_add_co_u32_e32 v14, vcc, 0x930000, v12
	s_nop 1
	v_addc_co_u32_e32 v15, vcc, 0, v13, vcc
	global_load_dword v102, v[14:15], off
	v_add_co_u32_e32 v14, vcc, 0x948000, v12
	s_nop 1
	v_addc_co_u32_e32 v15, vcc, 0, v13, vcc
	global_load_dword v103, v[14:15], off
	v_add_co_u32_e32 v14, vcc, 0x960000, v12
	s_nop 1
	v_addc_co_u32_e32 v15, vcc, 0, v13, vcc
	global_load_dword v104, v[14:15], off
	v_add_co_u32_e32 v14, vcc, 0x978000, v12
	s_nop 1
	v_addc_co_u32_e32 v15, vcc, 0, v13, vcc
	global_load_dword v105, v[14:15], off
	v_add_co_u32_e32 v14, vcc, 0x990000, v12
	s_nop 1
	v_addc_co_u32_e32 v15, vcc, 0, v13, vcc
	global_load_dword v106, v[14:15], off
	v_add_co_u32_e32 v14, vcc, 0x9a8000, v12
	s_nop 1
	v_addc_co_u32_e32 v15, vcc, 0, v13, vcc
	global_load_dword v107, v[14:15], off
	v_add_co_u32_e32 v14, vcc, 0x9c0000, v12
	s_nop 1
	v_addc_co_u32_e32 v15, vcc, 0, v13, vcc
	global_load_dword v108, v[14:15], off
	v_add_co_u32_e32 v14, vcc, 0x9d8000, v12
	s_nop 1
	v_addc_co_u32_e32 v15, vcc, 0, v13, vcc
	global_load_dword v109, v[14:15], off
	v_add_co_u32_e32 v14, vcc, 0x9f0000, v12
	s_nop 1
	v_addc_co_u32_e32 v15, vcc, 0, v13, vcc
	global_load_dword v110, v[14:15], off
	v_add_co_u32_e32 v14, vcc, 0xa08000, v12
	s_nop 1
	v_addc_co_u32_e32 v15, vcc, 0, v13, vcc
	global_load_dword v111, v[14:15], off
	v_add_co_u32_e32 v14, vcc, 0xa20000, v12
	s_nop 1
	v_addc_co_u32_e32 v15, vcc, 0, v13, vcc
	global_load_dword v112, v[14:15], off
	v_add_co_u32_e32 v14, vcc, 0xa38000, v12
	s_nop 1
	v_addc_co_u32_e32 v15, vcc, 0, v13, vcc
	global_load_dword v113, v[14:15], off
	v_add_co_u32_e32 v14, vcc, 0xa50000, v12
	s_nop 1
	v_addc_co_u32_e32 v15, vcc, 0, v13, vcc
	global_load_dword v114, v[14:15], off
	v_add_co_u32_e32 v14, vcc, 0xa68000, v12
	s_nop 1
	v_addc_co_u32_e32 v15, vcc, 0, v13, vcc
	global_load_dword v115, v[14:15], off
	s_waitcnt vmcnt(15)
	v_mul_f32_e32 v21, v19, v100
	s_waitcnt vmcnt(14)
	v_mul_f32_e32 v14, v19, v101
	ds_write2_b32 v32, v21, v14 offset0:32 offset1:97
	s_waitcnt vmcnt(13)
	v_mul_f32_e32 v21, v19, v102
	s_waitcnt vmcnt(12)
	v_mul_f32_e32 v14, v19, v103
	ds_write2_b32 v32, v21, v14 offset0:162 offset1:227
	s_waitcnt vmcnt(11)
	v_mul_f32_e32 v21, v19, v104
	s_waitcnt vmcnt(10)
	v_mul_f32_e32 v14, v19, v105
	ds_write2_b32 v29, v21, v14 offset0:36 offset1:101
	s_waitcnt vmcnt(9)
	v_mul_f32_e32 v21, v19, v106
	s_waitcnt vmcnt(8)
	v_mul_f32_e32 v14, v19, v107
	ds_write2_b32 v29, v21, v14 offset0:166 offset1:231
	s_waitcnt vmcnt(7)
	v_mul_f32_e32 v21, v19, v108
	s_waitcnt vmcnt(6)
	v_mul_f32_e32 v14, v19, v109
	ds_write2_b32 v30, v21, v14 offset0:40 offset1:105
	s_waitcnt vmcnt(5)
; __device__ __forceinline__ unsigned f2bf(float f) { unsigned u = __builtin_bit_cast(unsigned, f); return (u + 0x7fffu + ((u >> 16) & 1u)) >> 16; }
; #define LDS_WAIT() asm volatile("s_waitcnt lgkmcnt(0)" ::: "memory")
; __device__ __forceinline__ void hyena_norm(const float* ZT, const float* gain, bf16* mixed, LAS unsigned char* lds, int vb, int nb, int wave, int lane) {
;     ...
;             for (int cc = 0; cc < 64; ++cc) tile[cc * 65 + lane] = src[(size_t)(cb * 64 + cc) * MTOK] * rstd;
;             LDS_WAIT();
;             const float gv = gain[c0 + lane];
;             for (int i = 0; i < 64; ++i) mixed[(size_t)(R0 + i) * DM + 1024 + c0 + lane] = (bf16)f2bf(tile[lane * 65 + i] * gv);
;             LDS_WAIT();
	v_mul_f32_e32 v21, v19, v110
	s_waitcnt vmcnt(4)
	v_mul_f32_e32 v14, v19, v111
	ds_write2_b32 v30, v21, v14 offset0:170 offset1:235
	s_waitcnt vmcnt(3)
	v_mul_f32_e32 v21, v19, v112
	s_waitcnt vmcnt(2)
	v_mul_f32_e32 v14, v19, v113
	ds_write2_b32 v27, v21, v14 offset0:44 offset1:109
	s_waitcnt vmcnt(1)
	v_mul_f32_e32 v21, v19, v114
	s_waitcnt vmcnt(0)
	v_mul_f32_e32 v14, v19, v115
	ds_write2_b32 v27, v21, v14 offset0:174 offset1:239
	v_add_co_u32_e32 v14, vcc, 0xa80000, v12
	s_nop 1
	v_addc_co_u32_e32 v15, vcc, 0, v13, vcc
	global_load_dword v100, v[14:15], off
	v_add_co_u32_e32 v14, vcc, 0xa98000, v12
	s_nop 1
	v_addc_co_u32_e32 v15, vcc, 0, v13, vcc
	global_load_dword v101, v[14:15], off
	v_add_co_u32_e32 v14, vcc, 0xab0000, v12
	s_nop 1
	v_addc_co_u32_e32 v15, vcc, 0, v13, vcc
	global_load_dword v102, v[14:15], off
	v_add_co_u32_e32 v14, vcc, 0xac8000, v12
	s_nop 1
	v_addc_co_u32_e32 v15, vcc, 0, v13, vcc
	global_load_dword v103, v[14:15], off
	v_add_co_u32_e32 v14, vcc, 0xae0000, v12
	s_nop 1
	v_addc_co_u32_e32 v15, vcc, 0, v13, vcc
	global_load_dword v104, v[14:15], off
	v_add_co_u32_e32 v14, vcc, 0xaf8000, v12
	s_nop 1
	v_addc_co_u32_e32 v15, vcc, 0, v13, vcc
	global_load_dword v105, v[14:15], off
	v_add_co_u32_e32 v14, vcc, 0xb10000, v12
	s_nop 1
	v_addc_co_u32_e32 v15, vcc, 0, v13, vcc
	global_load_dword v106, v[14:15], off
	v_add_co_u32_e32 v14, vcc, 0xb28000, v12
	s_nop 1
	v_addc_co_u32_e32 v15, vcc, 0, v13, vcc
	global_load_dword v107, v[14:15], off
	v_add_co_u32_e32 v14, vcc, 0xb40000, v12
	s_nop 1
	v_addc_co_u32_e32 v15, vcc, 0, v13, vcc
	global_load_dword v108, v[14:15], off
	v_add_co_u32_e32 v14, vcc, 0xb58000, v12
	s_nop 1
	v_addc_co_u32_e32 v15, vcc, 0, v13, vcc
	global_load_dword v109, v[14:15], off
	v_add_co_u32_e32 v14, vcc, 0xb70000, v12
	s_nop 1
	v_addc_co_u32_e32 v15, vcc, 0, v13, vcc
	global_load_dword v110, v[14:15], off
	v_add_co_u32_e32 v14, vcc, 0xb88000, v12
	s_nop 1
	v_addc_co_u32_e32 v15, vcc, 0, v13, vcc
	global_load_dword v111, v[14:15], off
	v_add_co_u32_e32 v14, vcc, 0xba0000, v12
	s_nop 1
	v_addc_co_u32_e32 v15, vcc, 0, v13, vcc
	global_load_dword v112, v[14:15], off
	v_add_co_u32_e32 v14, vcc, 0xbb8000, v12
	s_nop 1
	v_addc_co_u32_e32 v15, vcc, 0, v13, vcc
	global_load_dword v113, v[14:15], off
	v_add_co_u32_e32 v14, vcc, 0xbd0000, v12
	s_nop 1
	v_addc_co_u32_e32 v15, vcc, 0, v13, vcc
	v_add_co_u32_e32 v12, vcc, 0xbe8000, v12
	global_load_dword v114, v[14:15], off
	s_nop 0
	v_addc_co_u32_e32 v13, vcc, 0, v13, vcc
	global_load_dword v115, v[12:13], off
	s_waitcnt vmcnt(15)
	v_mul_f32_e32 v21, v19, v100
	s_waitcnt vmcnt(14)
	v_mul_f32_e32 v14, v19, v101
	ds_write2_b32 v28, v21, v14 offset0:48 offset1:113
	s_waitcnt vmcnt(13)
	v_mul_f32_e32 v21, v19, v102
	s_waitcnt vmcnt(12)
	v_mul_f32_e32 v14, v19, v103
	ds_write2_b32 v28, v21, v14 offset0:178 offset1:243
	s_waitcnt vmcnt(11)
	v_mul_f32_e32 v21, v19, v104
	s_waitcnt vmcnt(10)
	v_mul_f32_e32 v14, v19, v105
	ds_write2_b32 v25, v21, v14 offset0:52 offset1:117
	s_waitcnt vmcnt(9)
	v_mul_f32_e32 v21, v19, v106
	s_waitcnt vmcnt(8)
	v_mul_f32_e32 v14, v19, v107
	ds_write2_b32 v25, v21, v14 offset0:182 offset1:247
	s_waitcnt vmcnt(7)
	v_mul_f32_e32 v21, v19, v108
	s_waitcnt vmcnt(6)
	v_mul_f32_e32 v14, v19, v109
	ds_write2_b32 v26, v21, v14 offset0:56 offset1:121
	s_waitcnt vmcnt(5)
	v_mul_f32_e32 v21, v19, v110
	s_waitcnt vmcnt(4)
	v_mul_f32_e32 v14, v19, v111
	ds_write2_b32 v26, v21, v14 offset0:186 offset1:251
	s_waitcnt vmcnt(3)
	v_mul_f32_e32 v21, v19, v112
	s_waitcnt vmcnt(2)
	v_mul_f32_e32 v14, v19, v113
	ds_write2_b32 v20, v21, v14 offset0:60 offset1:125
	s_waitcnt vmcnt(1)
	v_mul_f32_e32 v14, v19, v114
	s_waitcnt vmcnt(0)
	v_mul_f32_e32 v12, v19, v115
	ds_write2_b32 v20, v14, v12 offset0:190 offset1:255
	s_waitcnt lgkmcnt(0)
	global_load_dword v12, v[8:9], off offset:256
	s_waitcnt vmcnt(0)
	v_mov_b32_e32 v13, v12
